# P0 hand-pipelined fast path (x->fp8, rope, w_in transpose) v1
# baseline (speedup 1.0000x reference)
; __device__ __forceinline__ unsigned cvt_pk_bf16(float lo, float hi) { unsigned r; asm volatile("v_cvt_pk_bf16_f32 %0, %1, %2" : "=v"(r) : "v"(lo), "v"(hi)); return r; }
; __global__ void __launch_bounds__(512, 2) hybrid_fwd(Args a) {
;     ...
;         const size_t gt = (size_t)bx * 512 + tid, GT = (size_t)G * 512;
;         {
;             const size_t NCH = (size_t)M * D / 8;
;             for (size_t i0 = gt; i0 < NCH; i0 += 4 * GT) {
;                 f32x4 v[4][2];
; #pragma unroll
;                 for (int u = 0; u < 4; ++u) { const size_t i = i0 + (size_t)u * GT; if (i < NCH) { v[u][0] = ((const f32x4*)a.x)[2 * i]; v[u][1] = ((const f32x4*)a.x)[2 * i + 1]; } }
; #pragma unroll
;                 for (int u = 0; u < 4; ++u) { const size_t i = i0 + (size_t)u * GT; if (i < NCH) {
;                     u32x4 w; w.x = cvt_pk_bf16(v[u][0][0], v[u][0][1]); w.y = cvt_pk_bf16(v[u][0][2], v[u][0][3]); w.z = cvt_pk_bf16(v[u][1][0], v[u][1][1]); w.w = cvt_pk_bf16(v[u][1][2], v[u][1][3]);
;                     if (a.n_bf16 > 0) ((u32x4*)XB)[i] = w;
;                     const unsigned p0 = pack_fp8x4(v[u][0][0], v[u][0][1], v[u][0][2], v[u][0][3]), p1 = pack_fp8x4(v[u][1][0], v[u][1][1], v[u][1][2], v[u][1][3]);
;                     ((u32x2*)XB8)[i] = (u32x2){p0, p1}; } }
.LBB0_2:
	s_or_b64 exec, exec, s[4:5]
	s_ashr_i32 s3, s2, 31
	s_lshl_b64 s[4:5], s[2:3], 9
	v_mov_b32_e32 v161, 0
	v_lshl_add_u64 v[38:39], s[4:5], 0, v[160:161]
	s_waitcnt lgkmcnt(0)
	s_ashr_i32 s93, s92, 31
	s_mov_b64 s[12:13], 0x400000
	s_lshl_b64 s[14:15], s[92:93], 9
	v_cmp_gt_u64_e32 vcc, s[12:13], v[38:39]
	v_lshlrev_b32_e32 v40, 3, v160
	s_mov_b32 s100, 0
	s_cmp_lg_u32 s92, 0x100
	s_cbranch_scc1 .Lp0_done
	s_load_dword s16, s[70:71], 0x1c0
	s_load_dwordx2 s[18:19], s[70:71], 0x1c8
	s_load_dwordx2 s[6:7], s[70:71], 0x0
	s_load_dwordx2 s[20:21], s[70:71], 0x8
	s_load_dwordx2 s[22:23], s[70:71], 0x10
	s_waitcnt lgkmcnt(0)
	s_cmp_lg_u32 s16, 0
	s_cbranch_scc1 .Lp0_done
	s_cmp_lg_u32 s18, -1
	s_cbranch_scc1 .Lp0_done
	s_cmpk_lg_u32 s19, 0x1fff
	s_cbranch_scc1 .Lp0_done
	v_lshl_add_u32 v1, s2, 9, v160
	v_and_b32_e32 v4, 63, v160
	v_lshlrev_b32_e32 v2, 5, v1
	v_lshlrev_b32_e32 v3, 3, v1
	s_mov_b64 s[8:9], s[88:89]
	global_load_dwordx4 v[64:67], v2, s[6:7]
	global_load_dwordx4 v[68:71], v2, s[6:7] offset:16
	s_add_u32 s6, s6, 0x400000
	s_addc_u32 s7, s7, 0
	global_load_dwordx4 v[72:75], v2, s[6:7]
	global_load_dwordx4 v[76:79], v2, s[6:7] offset:16
	s_add_u32 s6, s6, 0x400000
	s_addc_u32 s7, s7, 0
	global_load_dwordx4 v[80:83], v2, s[6:7]
	global_load_dwordx4 v[84:87], v2, s[6:7] offset:16
	s_add_u32 s6, s6, 0x400000
	s_addc_u32 s7, s7, 0
	global_load_dwordx4 v[88:91], v2, s[6:7]
	global_load_dwordx4 v[92:95], v2, s[6:7] offset:16
	s_add_u32 s6, s6, 0x400000
	s_addc_u32 s7, s7, 0
	global_load_dwordx4 v[96:99], v2, s[6:7]
	global_load_dwordx4 v[100:103], v2, s[6:7] offset:16
	s_add_u32 s6, s6, 0x400000
	s_addc_u32 s7, s7, 0
	global_load_dwordx4 v[104:107], v2, s[6:7]
	global_load_dwordx4 v[108:111], v2, s[6:7] offset:16
	s_add_u32 s6, s6, 0x400000
	s_addc_u32 s7, s7, 0
	global_load_dwordx4 v[112:115], v2, s[6:7]
	global_load_dwordx4 v[116:119], v2, s[6:7] offset:16
	s_add_u32 s6, s6, 0x400000
	s_addc_u32 s7, s7, 0
	global_load_dwordx4 v[120:123], v2, s[6:7]
	global_load_dwordx4 v[124:127], v2, s[6:7] offset:16
	s_add_u32 s6, s6, 0x400000
	s_addc_u32 s7, s7, 0
	s_waitcnt vmcnt(14)
	v_cvt_pk_fp8_f32 v8, v64, v65
	v_cvt_pk_fp8_f32 v9, v66, v67
	v_cvt_pk_fp8_f32 v10, v68, v69
	v_cvt_pk_fp8_f32 v11, v70, v71
	v_and_b32_e32 v8, 0xffff, v8
	v_and_b32_e32 v10, 0xffff, v10
	v_lshl_or_b32 v128, v9, 16, v8
	v_lshl_or_b32 v129, v11, 16, v10
	global_store_dwordx2 v3, v[128:129], s[8:9]
	s_add_u32 s8, s8, 0x100000
	s_addc_u32 s9, s9, 0
	global_load_dwordx4 v[64:67], v2, s[6:7]
	global_load_dwordx4 v[68:71], v2, s[6:7] offset:16
	s_add_u32 s6, s6, 0x400000
	s_addc_u32 s7, s7, 0
	s_waitcnt vmcnt(15)
	v_cvt_pk_fp8_f32 v8, v72, v73
	v_cvt_pk_fp8_f32 v9, v74, v75
	v_cvt_pk_fp8_f32 v10, v76, v77
	v_cvt_pk_fp8_f32 v11, v78, v79
	v_and_b32_e32 v8, 0xffff, v8
	v_and_b32_e32 v10, 0xffff, v10
	v_lshl_or_b32 v130, v9, 16, v8
	v_lshl_or_b32 v131, v11, 16, v10
	global_store_dwordx2 v3, v[130:131], s[8:9]
	s_add_u32 s8, s8, 0x100000
	s_addc_u32 s9, s9, 0
	global_load_dwordx4 v[72:75], v2, s[6:7]
	global_load_dwordx4 v[76:79], v2, s[6:7] offset:16
	s_add_u32 s6, s6, 0x400000
	s_addc_u32 s7, s7, 0
	s_waitcnt vmcnt(16)
	v_cvt_pk_fp8_f32 v8, v80, v81
	v_cvt_pk_fp8_f32 v9, v82, v83
	v_cvt_pk_fp8_f32 v10, v84, v85
	v_cvt_pk_fp8_f32 v11, v86, v87
	v_and_b32_e32 v8, 0xffff, v8
	v_and_b32_e32 v10, 0xffff, v10
	v_lshl_or_b32 v132, v9, 16, v8
	v_lshl_or_b32 v133, v11, 16, v10
	global_store_dwordx2 v3, v[132:133], s[8:9]
	s_add_u32 s8, s8, 0x100000
	s_addc_u32 s9, s9, 0
	global_load_dwordx4 v[80:83], v2, s[6:7]
	global_load_dwordx4 v[84:87], v2, s[6:7] offset:16
	s_add_u32 s6, s6, 0x400000
	s_addc_u32 s7, s7, 0
	s_waitcnt vmcnt(17)
	v_cvt_pk_fp8_f32 v8, v88, v89
	v_cvt_pk_fp8_f32 v9, v90, v91
	v_cvt_pk_fp8_f32 v10, v92, v93
	v_cvt_pk_fp8_f32 v11, v94, v95
	v_and_b32_e32 v8, 0xffff, v8
	v_and_b32_e32 v10, 0xffff, v10
	v_lshl_or_b32 v134, v9, 16, v8
	v_lshl_or_b32 v135, v11, 16, v10
	global_store_dwordx2 v3, v[134:135], s[8:9]
	s_add_u32 s8, s8, 0x100000
	s_addc_u32 s9, s9, 0
	global_load_dwordx4 v[88:91], v2, s[6:7]
	global_load_dwordx4 v[92:95], v2, s[6:7] offset:16
	s_add_u32 s6, s6, 0x400000
	s_addc_u32 s7, s7, 0
	s_waitcnt vmcnt(18)
	v_cvt_pk_fp8_f32 v8, v96, v97
	v_cvt_pk_fp8_f32 v9, v98, v99
	v_cvt_pk_fp8_f32 v10, v100, v101
	v_cvt_pk_fp8_f32 v11, v102, v103
	v_and_b32_e32 v8, 0xffff, v8
	v_and_b32_e32 v10, 0xffff, v10
	v_lshl_or_b32 v136, v9, 16, v8
	v_lshl_or_b32 v137, v11, 16, v10
	global_store_dwordx2 v3, v[136:137], s[8:9]
	s_add_u32 s8, s8, 0x100000
	s_addc_u32 s9, s9, 0
	global_load_dwordx4 v[96:99], v2, s[6:7]
	global_load_dwordx4 v[100:103], v2, s[6:7] offset:16
	s_add_u32 s6, s6, 0x400000
	s_addc_u32 s7, s7, 0
	s_waitcnt vmcnt(19)
	v_cvt_pk_fp8_f32 v8, v104, v105
	v_cvt_pk_fp8_f32 v9, v106, v107
	v_cvt_pk_fp8_f32 v10, v108, v109
	v_cvt_pk_fp8_f32 v11, v110, v111
	v_and_b32_e32 v8, 0xffff, v8
	v_and_b32_e32 v10, 0xffff, v10
	v_lshl_or_b32 v138, v9, 16, v8
	v_lshl_or_b32 v139, v11, 16, v10
	global_store_dwordx2 v3, v[138:139], s[8:9]
	s_add_u32 s8, s8, 0x100000
	s_addc_u32 s9, s9, 0
	global_load_dwordx4 v[104:107], v2, s[6:7]
	global_load_dwordx4 v[108:111], v2, s[6:7] offset:16
	s_add_u32 s6, s6, 0x400000
	s_addc_u32 s7, s7, 0
	s_waitcnt vmcnt(20)
	v_cvt_pk_fp8_f32 v8, v112, v113
	v_cvt_pk_fp8_f32 v9, v114, v115
	v_cvt_pk_fp8_f32 v10, v116, v117
	v_cvt_pk_fp8_f32 v11, v118, v119
	v_and_b32_e32 v8, 0xffff, v8
	v_and_b32_e32 v10, 0xffff, v10
	v_lshl_or_b32 v140, v9, 16, v8
	v_lshl_or_b32 v141, v11, 16, v10
	global_store_dwordx2 v3, v[140:141], s[8:9]
	s_add_u32 s8, s8, 0x100000
	s_addc_u32 s9, s9, 0
	global_load_dwordx4 v[112:115], v2, s[6:7]
	global_load_dwordx4 v[116:119], v2, s[6:7] offset:16
	s_add_u32 s6, s6, 0x400000
	s_addc_u32 s7, s7, 0
	s_waitcnt vmcnt(21)
; __device__ __forceinline__ unsigned cvt_pk_bf16(float lo, float hi) { unsigned r; asm volatile("v_cvt_pk_bf16_f32 %0, %1, %2" : "=v"(r) : "v"(lo), "v"(hi)); return r; }
; __global__ void __launch_bounds__(512, 2) hybrid_fwd(Args a) {
;     ...
;             for (size_t i0 = gt; i0 < NCH; i0 += 4 * GT) {
;                 f32x4 v[4][2];
; #pragma unroll
;                 for (int u = 0; u < 4; ++u) { const size_t i = i0 + (size_t)u * GT; if (i < NCH) { v[u][0] = ((const f32x4*)a.x)[2 * i]; v[u][1] = ((const f32x4*)a.x)[2 * i + 1]; } }
; #pragma unroll
;                 for (int u = 0; u < 4; ++u) { const size_t i = i0 + (size_t)u * GT; if (i < NCH) {
;                     u32x4 w; w.x = cvt_pk_bf16(v[u][0][0], v[u][0][1]); w.y = cvt_pk_bf16(v[u][0][2], v[u][0][3]); w.z = cvt_pk_bf16(v[u][1][0], v[u][1][1]); w.w = cvt_pk_bf16(v[u][1][2], v[u][1][3]);
;                     if (a.n_bf16 > 0) ((u32x4*)XB)[i] = w;
;                     const unsigned p0 = pack_fp8x4(v[u][0][0], v[u][0][1], v[u][0][2], v[u][0][3]), p1 = pack_fp8x4(v[u][1][0], v[u][1][1], v[u][1][2], v[u][1][3]);
;                     ((u32x2*)XB8)[i] = (u32x2){p0, p1}; } }
	v_cvt_pk_fp8_f32 v8, v120, v121
	v_cvt_pk_fp8_f32 v9, v122, v123
	v_cvt_pk_fp8_f32 v10, v124, v125
	v_cvt_pk_fp8_f32 v11, v126, v127
	v_and_b32_e32 v8, 0xffff, v8
	v_and_b32_e32 v10, 0xffff, v10
	v_lshl_or_b32 v142, v9, 16, v8
	v_lshl_or_b32 v143, v11, 16, v10
	global_store_dwordx2 v3, v[142:143], s[8:9]
	s_add_u32 s8, s8, 0x100000
	s_addc_u32 s9, s9, 0
	global_load_dwordx4 v[120:123], v2, s[6:7]
	global_load_dwordx4 v[124:127], v2, s[6:7] offset:16
	s_add_u32 s6, s6, 0x400000
	s_addc_u32 s7, s7, 0
	s_waitcnt vmcnt(21)
	v_cvt_pk_fp8_f32 v8, v64, v65
	v_cvt_pk_fp8_f32 v9, v66, v67
	v_cvt_pk_fp8_f32 v10, v68, v69
	v_cvt_pk_fp8_f32 v11, v70, v71
	v_and_b32_e32 v8, 0xffff, v8
	v_and_b32_e32 v10, 0xffff, v10
	v_lshl_or_b32 v128, v9, 16, v8
	v_lshl_or_b32 v129, v11, 16, v10
	global_store_dwordx2 v3, v[128:129], s[8:9]
	s_add_u32 s8, s8, 0x100000
	s_addc_u32 s9, s9, 0
	global_load_dwordx4 v[64:67], v2, s[6:7]
	global_load_dwordx4 v[68:71], v2, s[6:7] offset:16
	s_add_u32 s6, s6, 0x400000
	s_addc_u32 s7, s7, 0
	s_waitcnt vmcnt(21)
	v_cvt_pk_fp8_f32 v8, v72, v73
	v_cvt_pk_fp8_f32 v9, v74, v75
	v_cvt_pk_fp8_f32 v10, v76, v77
	v_cvt_pk_fp8_f32 v11, v78, v79
	v_and_b32_e32 v8, 0xffff, v8
	v_and_b32_e32 v10, 0xffff, v10
	v_lshl_or_b32 v130, v9, 16, v8
	v_lshl_or_b32 v131, v11, 16, v10
	global_store_dwordx2 v3, v[130:131], s[8:9]
	s_add_u32 s8, s8, 0x100000
	s_addc_u32 s9, s9, 0
	global_load_dwordx4 v[72:75], v2, s[6:7]
	global_load_dwordx4 v[76:79], v2, s[6:7] offset:16
	s_add_u32 s6, s6, 0x400000
	s_addc_u32 s7, s7, 0
	s_waitcnt vmcnt(21)
	v_cvt_pk_fp8_f32 v8, v80, v81
	v_cvt_pk_fp8_f32 v9, v82, v83
	v_cvt_pk_fp8_f32 v10, v84, v85
	v_cvt_pk_fp8_f32 v11, v86, v87
	v_and_b32_e32 v8, 0xffff, v8
	v_and_b32_e32 v10, 0xffff, v10
	v_lshl_or_b32 v132, v9, 16, v8
	v_lshl_or_b32 v133, v11, 16, v10
	global_store_dwordx2 v3, v[132:133], s[8:9]
	s_add_u32 s8, s8, 0x100000
	s_addc_u32 s9, s9, 0
	global_load_dwordx4 v[80:83], v2, s[6:7]
	global_load_dwordx4 v[84:87], v2, s[6:7] offset:16
	s_add_u32 s6, s6, 0x400000
	s_addc_u32 s7, s7, 0
	s_waitcnt vmcnt(21)
	v_cvt_pk_fp8_f32 v8, v88, v89
	v_cvt_pk_fp8_f32 v9, v90, v91
	v_cvt_pk_fp8_f32 v10, v92, v93
	v_cvt_pk_fp8_f32 v11, v94, v95
	v_and_b32_e32 v8, 0xffff, v8
	v_and_b32_e32 v10, 0xffff, v10
	v_lshl_or_b32 v134, v9, 16, v8
	v_lshl_or_b32 v135, v11, 16, v10
	global_store_dwordx2 v3, v[134:135], s[8:9]
	s_add_u32 s8, s8, 0x100000
	s_addc_u32 s9, s9, 0
	global_load_dwordx4 v[88:91], v2, s[6:7]
	global_load_dwordx4 v[92:95], v2, s[6:7] offset:16
	s_add_u32 s6, s6, 0x400000
	s_addc_u32 s7, s7, 0
	s_waitcnt vmcnt(21)
	v_cvt_pk_fp8_f32 v8, v96, v97
	v_cvt_pk_fp8_f32 v9, v98, v99
	v_cvt_pk_fp8_f32 v10, v100, v101
	v_cvt_pk_fp8_f32 v11, v102, v103
	v_and_b32_e32 v8, 0xffff, v8
	v_and_b32_e32 v10, 0xffff, v10
	v_lshl_or_b32 v136, v9, 16, v8
	v_lshl_or_b32 v137, v11, 16, v10
	global_store_dwordx2 v3, v[136:137], s[8:9]
	s_add_u32 s8, s8, 0x100000
	s_addc_u32 s9, s9, 0
	global_load_dwordx4 v[96:99], v2, s[6:7]
	global_load_dwordx4 v[100:103], v2, s[6:7] offset:16
	s_add_u32 s6, s6, 0x400000
	s_addc_u32 s7, s7, 0
	s_waitcnt vmcnt(21)
	v_cvt_pk_fp8_f32 v8, v104, v105
	v_cvt_pk_fp8_f32 v9, v106, v107
	v_cvt_pk_fp8_f32 v10, v108, v109
	v_cvt_pk_fp8_f32 v11, v110, v111
	v_and_b32_e32 v8, 0xffff, v8
	v_and_b32_e32 v10, 0xffff, v10
	v_lshl_or_b32 v138, v9, 16, v8
	v_lshl_or_b32 v139, v11, 16, v10
	global_store_dwordx2 v3, v[138:139], s[8:9]
	s_add_u32 s8, s8, 0x100000
	s_addc_u32 s9, s9, 0
	global_load_dwordx4 v[104:107], v2, s[6:7]
	global_load_dwordx4 v[108:111], v2, s[6:7] offset:16
	s_add_u32 s6, s6, 0x400000
	s_addc_u32 s7, s7, 0
	s_waitcnt vmcnt(21)
	v_cvt_pk_fp8_f32 v8, v112, v113
	v_cvt_pk_fp8_f32 v9, v114, v115
	v_cvt_pk_fp8_f32 v10, v116, v117
	v_cvt_pk_fp8_f32 v11, v118, v119
	v_and_b32_e32 v8, 0xffff, v8
	v_and_b32_e32 v10, 0xffff, v10
	v_lshl_or_b32 v140, v9, 16, v8
	v_lshl_or_b32 v141, v11, 16, v10
	global_store_dwordx2 v3, v[140:141], s[8:9]
	s_add_u32 s8, s8, 0x100000
	s_addc_u32 s9, s9, 0
	global_load_dwordx4 v[112:115], v2, s[6:7]
	global_load_dwordx4 v[116:119], v2, s[6:7] offset:16
	s_add_u32 s6, s6, 0x400000
	s_addc_u32 s7, s7, 0
	s_waitcnt vmcnt(21)
	v_cvt_pk_fp8_f32 v8, v120, v121
	v_cvt_pk_fp8_f32 v9, v122, v123
	v_cvt_pk_fp8_f32 v10, v124, v125
	v_cvt_pk_fp8_f32 v11, v126, v127
	v_and_b32_e32 v8, 0xffff, v8
	v_and_b32_e32 v10, 0xffff, v10
	v_lshl_or_b32 v142, v9, 16, v8
	v_lshl_or_b32 v143, v11, 16, v10
	global_store_dwordx2 v3, v[142:143], s[8:9]
	s_add_u32 s8, s8, 0x100000
	s_addc_u32 s9, s9, 0
	global_load_dwordx4 v[120:123], v2, s[6:7]
	global_load_dwordx4 v[124:127], v2, s[6:7] offset:16
	s_add_u32 s6, s6, 0x400000
	s_addc_u32 s7, s7, 0
	s_waitcnt vmcnt(21)
	v_cvt_pk_fp8_f32 v8, v64, v65
	v_cvt_pk_fp8_f32 v9, v66, v67
	v_cvt_pk_fp8_f32 v10, v68, v69
	v_cvt_pk_fp8_f32 v11, v70, v71
	v_and_b32_e32 v8, 0xffff, v8
	v_and_b32_e32 v10, 0xffff, v10
	v_lshl_or_b32 v128, v9, 16, v8
	v_lshl_or_b32 v129, v11, 16, v10
	global_store_dwordx2 v3, v[128:129], s[8:9]
	s_add_u32 s8, s8, 0x100000
	s_addc_u32 s9, s9, 0
	global_load_dwordx4 v[64:67], v2, s[6:7]
	global_load_dwordx4 v[68:71], v2, s[6:7] offset:16
	s_add_u32 s6, s6, 0x400000
	s_addc_u32 s7, s7, 0
	s_waitcnt vmcnt(21)
	v_cvt_pk_fp8_f32 v8, v72, v73
	v_cvt_pk_fp8_f32 v9, v74, v75
	v_cvt_pk_fp8_f32 v10, v76, v77
	v_cvt_pk_fp8_f32 v11, v78, v79
	v_and_b32_e32 v8, 0xffff, v8
	v_and_b32_e32 v10, 0xffff, v10
	v_lshl_or_b32 v130, v9, 16, v8
	v_lshl_or_b32 v131, v11, 16, v10
	global_store_dwordx2 v3, v[130:131], s[8:9]
	s_add_u32 s8, s8, 0x100000
	s_addc_u32 s9, s9, 0
	global_load_dwordx4 v[72:75], v2, s[6:7]
	global_load_dwordx4 v[76:79], v2, s[6:7] offset:16
	s_add_u32 s6, s6, 0x400000
	s_addc_u32 s7, s7, 0
	s_waitcnt vmcnt(21)
; __device__ __forceinline__ unsigned cvt_pk_bf16(float lo, float hi) { unsigned r; asm volatile("v_cvt_pk_bf16_f32 %0, %1, %2" : "=v"(r) : "v"(lo), "v"(hi)); return r; }
; __global__ void __launch_bounds__(512, 2) hybrid_fwd(Args a) {
;     ...
;             for (size_t i0 = gt; i0 < NCH; i0 += 4 * GT) {
;                 f32x4 v[4][2];
; #pragma unroll
;                 for (int u = 0; u < 4; ++u) { const size_t i = i0 + (size_t)u * GT; if (i < NCH) { v[u][0] = ((const f32x4*)a.x)[2 * i]; v[u][1] = ((const f32x4*)a.x)[2 * i + 1]; } }
; #pragma unroll
;                 for (int u = 0; u < 4; ++u) { const size_t i = i0 + (size_t)u * GT; if (i < NCH) {
;                     u32x4 w; w.x = cvt_pk_bf16(v[u][0][0], v[u][0][1]); w.y = cvt_pk_bf16(v[u][0][2], v[u][0][3]); w.z = cvt_pk_bf16(v[u][1][0], v[u][1][1]); w.w = cvt_pk_bf16(v[u][1][2], v[u][1][3]);
;                     if (a.n_bf16 > 0) ((u32x4*)XB)[i] = w;
;                     const unsigned p0 = pack_fp8x4(v[u][0][0], v[u][0][1], v[u][0][2], v[u][0][3]), p1 = pack_fp8x4(v[u][1][0], v[u][1][1], v[u][1][2], v[u][1][3]);
;                     ((u32x2*)XB8)[i] = (u32x2){p0, p1}; } }
	v_cvt_pk_fp8_f32 v8, v80, v81
	v_cvt_pk_fp8_f32 v9, v82, v83
	v_cvt_pk_fp8_f32 v10, v84, v85
	v_cvt_pk_fp8_f32 v11, v86, v87
	v_and_b32_e32 v8, 0xffff, v8
	v_and_b32_e32 v10, 0xffff, v10
	v_lshl_or_b32 v132, v9, 16, v8
	v_lshl_or_b32 v133, v11, 16, v10
	global_store_dwordx2 v3, v[132:133], s[8:9]
	s_add_u32 s8, s8, 0x100000
	s_addc_u32 s9, s9, 0
	global_load_dwordx4 v[80:83], v2, s[6:7]
	global_load_dwordx4 v[84:87], v2, s[6:7] offset:16
	s_add_u32 s6, s6, 0x400000
	s_addc_u32 s7, s7, 0
	s_waitcnt vmcnt(21)
	v_cvt_pk_fp8_f32 v8, v88, v89
	v_cvt_pk_fp8_f32 v9, v90, v91
	v_cvt_pk_fp8_f32 v10, v92, v93
	v_cvt_pk_fp8_f32 v11, v94, v95
	v_and_b32_e32 v8, 0xffff, v8
	v_and_b32_e32 v10, 0xffff, v10
	v_lshl_or_b32 v134, v9, 16, v8
	v_lshl_or_b32 v135, v11, 16, v10
	global_store_dwordx2 v3, v[134:135], s[8:9]
	s_add_u32 s8, s8, 0x100000
	s_addc_u32 s9, s9, 0
	global_load_dwordx4 v[88:91], v2, s[6:7]
	global_load_dwordx4 v[92:95], v2, s[6:7] offset:16
	s_add_u32 s6, s6, 0x400000
	s_addc_u32 s7, s7, 0
	s_waitcnt vmcnt(21)
	v_cvt_pk_fp8_f32 v8, v96, v97
	v_cvt_pk_fp8_f32 v9, v98, v99
	v_cvt_pk_fp8_f32 v10, v100, v101
	v_cvt_pk_fp8_f32 v11, v102, v103
	v_and_b32_e32 v8, 0xffff, v8
	v_and_b32_e32 v10, 0xffff, v10
	v_lshl_or_b32 v136, v9, 16, v8
	v_lshl_or_b32 v137, v11, 16, v10
	global_store_dwordx2 v3, v[136:137], s[8:9]
	s_add_u32 s8, s8, 0x100000
	s_addc_u32 s9, s9, 0
	global_load_dwordx4 v[96:99], v2, s[6:7]
	global_load_dwordx4 v[100:103], v2, s[6:7] offset:16
	s_add_u32 s6, s6, 0x400000
	s_addc_u32 s7, s7, 0
	s_waitcnt vmcnt(21)
	v_cvt_pk_fp8_f32 v8, v104, v105
	v_cvt_pk_fp8_f32 v9, v106, v107
	v_cvt_pk_fp8_f32 v10, v108, v109
	v_cvt_pk_fp8_f32 v11, v110, v111
	v_and_b32_e32 v8, 0xffff, v8
	v_and_b32_e32 v10, 0xffff, v10
	v_lshl_or_b32 v138, v9, 16, v8
	v_lshl_or_b32 v139, v11, 16, v10
	global_store_dwordx2 v3, v[138:139], s[8:9]
	s_add_u32 s8, s8, 0x100000
	s_addc_u32 s9, s9, 0
	global_load_dwordx4 v[104:107], v2, s[6:7]
	global_load_dwordx4 v[108:111], v2, s[6:7] offset:16
	s_add_u32 s6, s6, 0x400000
	s_addc_u32 s7, s7, 0
	s_waitcnt vmcnt(21)
	v_cvt_pk_fp8_f32 v8, v112, v113
	v_cvt_pk_fp8_f32 v9, v114, v115
	v_cvt_pk_fp8_f32 v10, v116, v117
	v_cvt_pk_fp8_f32 v11, v118, v119
	v_and_b32_e32 v8, 0xffff, v8
	v_and_b32_e32 v10, 0xffff, v10
	v_lshl_or_b32 v140, v9, 16, v8
	v_lshl_or_b32 v141, v11, 16, v10
	global_store_dwordx2 v3, v[140:141], s[8:9]
	s_add_u32 s8, s8, 0x100000
	s_addc_u32 s9, s9, 0
	global_load_dwordx4 v[112:115], v2, s[6:7]
	global_load_dwordx4 v[116:119], v2, s[6:7] offset:16
	s_add_u32 s6, s6, 0x400000
	s_addc_u32 s7, s7, 0
	s_waitcnt vmcnt(21)
	v_cvt_pk_fp8_f32 v8, v120, v121
	v_cvt_pk_fp8_f32 v9, v122, v123
	v_cvt_pk_fp8_f32 v10, v124, v125
	v_cvt_pk_fp8_f32 v11, v126, v127
	v_and_b32_e32 v8, 0xffff, v8
	v_and_b32_e32 v10, 0xffff, v10
	v_lshl_or_b32 v142, v9, 16, v8
	v_lshl_or_b32 v143, v11, 16, v10
	global_store_dwordx2 v3, v[142:143], s[8:9]
	s_add_u32 s8, s8, 0x100000
	s_addc_u32 s9, s9, 0
	global_load_dwordx4 v[120:123], v2, s[6:7]
	global_load_dwordx4 v[124:127], v2, s[6:7] offset:16
	s_add_u32 s6, s6, 0x400000
	s_addc_u32 s7, s7, 0
	s_waitcnt vmcnt(21)
	v_cvt_pk_fp8_f32 v8, v64, v65
	v_cvt_pk_fp8_f32 v9, v66, v67
	v_cvt_pk_fp8_f32 v10, v68, v69
	v_cvt_pk_fp8_f32 v11, v70, v71
	v_and_b32_e32 v8, 0xffff, v8
	v_and_b32_e32 v10, 0xffff, v10
	v_lshl_or_b32 v128, v9, 16, v8
	v_lshl_or_b32 v129, v11, 16, v10
	global_store_dwordx2 v3, v[128:129], s[8:9]
	s_add_u32 s8, s8, 0x100000
	s_addc_u32 s9, s9, 0
	s_waitcnt vmcnt(19)
	v_cvt_pk_fp8_f32 v8, v72, v73
	v_cvt_pk_fp8_f32 v9, v74, v75
	v_cvt_pk_fp8_f32 v10, v76, v77
	v_cvt_pk_fp8_f32 v11, v78, v79
	v_and_b32_e32 v8, 0xffff, v8
	v_and_b32_e32 v10, 0xffff, v10
	v_lshl_or_b32 v130, v9, 16, v8
	v_lshl_or_b32 v131, v11, 16, v10
	global_store_dwordx2 v3, v[130:131], s[8:9]
	s_add_u32 s8, s8, 0x100000
	s_addc_u32 s9, s9, 0
	s_waitcnt vmcnt(17)
	v_cvt_pk_fp8_f32 v8, v80, v81
	v_cvt_pk_fp8_f32 v9, v82, v83
	v_cvt_pk_fp8_f32 v10, v84, v85
	v_cvt_pk_fp8_f32 v11, v86, v87
	v_and_b32_e32 v8, 0xffff, v8
	v_and_b32_e32 v10, 0xffff, v10
	v_lshl_or_b32 v132, v9, 16, v8
	v_lshl_or_b32 v133, v11, 16, v10
	global_store_dwordx2 v3, v[132:133], s[8:9]
	s_add_u32 s8, s8, 0x100000
	s_addc_u32 s9, s9, 0
	s_waitcnt vmcnt(15)
	v_cvt_pk_fp8_f32 v8, v88, v89
	v_cvt_pk_fp8_f32 v9, v90, v91
	v_cvt_pk_fp8_f32 v10, v92, v93
	v_cvt_pk_fp8_f32 v11, v94, v95
	v_and_b32_e32 v8, 0xffff, v8
	v_and_b32_e32 v10, 0xffff, v10
	v_lshl_or_b32 v134, v9, 16, v8
	v_lshl_or_b32 v135, v11, 16, v10
	global_store_dwordx2 v3, v[134:135], s[8:9]
	s_add_u32 s8, s8, 0x100000
	s_addc_u32 s9, s9, 0
	s_waitcnt vmcnt(13)
	v_cvt_pk_fp8_f32 v8, v96, v97
	v_cvt_pk_fp8_f32 v9, v98, v99
	v_cvt_pk_fp8_f32 v10, v100, v101
	v_cvt_pk_fp8_f32 v11, v102, v103
	v_and_b32_e32 v8, 0xffff, v8
	v_and_b32_e32 v10, 0xffff, v10
	v_lshl_or_b32 v136, v9, 16, v8
	v_lshl_or_b32 v137, v11, 16, v10
	global_store_dwordx2 v3, v[136:137], s[8:9]
	s_add_u32 s8, s8, 0x100000
	s_addc_u32 s9, s9, 0
	s_waitcnt vmcnt(11)
	v_cvt_pk_fp8_f32 v8, v104, v105
	v_cvt_pk_fp8_f32 v9, v106, v107
	v_cvt_pk_fp8_f32 v10, v108, v109
	v_cvt_pk_fp8_f32 v11, v110, v111
	v_and_b32_e32 v8, 0xffff, v8
	v_and_b32_e32 v10, 0xffff, v10
	v_lshl_or_b32 v138, v9, 16, v8
	v_lshl_or_b32 v139, v11, 16, v10
	global_store_dwordx2 v3, v[138:139], s[8:9]
	s_add_u32 s8, s8, 0x100000
	s_addc_u32 s9, s9, 0
	s_waitcnt vmcnt(9)
	v_cvt_pk_fp8_f32 v8, v112, v113
	v_cvt_pk_fp8_f32 v9, v114, v115
	v_cvt_pk_fp8_f32 v10, v116, v117
	v_cvt_pk_fp8_f32 v11, v118, v119
	v_and_b32_e32 v8, 0xffff, v8
	v_and_b32_e32 v10, 0xffff, v10
	v_lshl_or_b32 v140, v9, 16, v8
	v_lshl_or_b32 v141, v11, 16, v10
	global_store_dwordx2 v3, v[140:141], s[8:9]
	s_add_u32 s8, s8, 0x100000
	s_addc_u32 s9, s9, 0
	s_waitcnt vmcnt(7)
; #define LAS __attribute__((address_space(3)))
; __device__ __forceinline__ void transpose_item_fp8(const float* W, int N, unsigned char* W8, int pitch, int kofs, int k0, int n_src, int n_dst, float scale, LAS float* scr, int lane) {
;     const int r8 = lane >> 3, c4 = lane & 7;
;     f32x4 v[8];
; #pragma unroll
;     for (int i = 0; i < 8; ++i) v[i] = *(const f32x4*)(W + (size_t)(k0 + r8 + 8 * i) * N + n_src + 4 * c4);
; #pragma unroll
;     for (int i = 0; i < 8; ++i) { LAS float* d = scr + (r8 + 8 * i) * 33 + 4 * c4; d[0] = v[i][0]; d[1] = v[i][1]; d[2] = v[i][2]; d[3] = v[i][3]; }
; __global__ void __launch_bounds__(512, 2) hybrid_fwd(Args a) {
;     ...
;         for (size_t i = gt; i < (size_t)M * 64; i += GT) {
;             const int t = (int)(i >> 6), j = (int)(i & 63);
;             const float ang = (float)a.pos[t] * a.inv_freq[j];
;             const double rev = (double)ang * 0.15915494309189535; const float fr = (float)(rev - __builtin_rint(rev));
;             const f32x2 cs = (f32x2){__builtin_amdgcn_cosf(fr), __builtin_amdgcn_sinf(fr)};
;             csB[i] = cs; if ((j & 1) == 0) csA[(size_t)t * 32 + (j >> 1)] = cs;
;         }
	v_cvt_pk_fp8_f32 v8, v120, v121
	v_cvt_pk_fp8_f32 v9, v122, v123
	v_cvt_pk_fp8_f32 v10, v124, v125
	v_cvt_pk_fp8_f32 v11, v126, v127
	v_and_b32_e32 v8, 0xffff, v8
	v_and_b32_e32 v10, 0xffff, v10
	v_lshl_or_b32 v142, v9, 16, v8
	v_lshl_or_b32 v143, v11, 16, v10
	global_store_dwordx2 v3, v[142:143], s[8:9]
	s_add_u32 s8, s8, 0x100000
	s_addc_u32 s9, s9, 0
	s_lshr_b32 s10, s33, 6
	s_lshl_b32 s11, s2, 3
	s_add_u32 s10, s10, s11
	s_lshl_b32 s11, s10, 2
	s_add_u32 s24, s20, s11
	s_addc_u32 s25, s21, 0
	s_load_dword s34, s[24:25], 0x0
	s_load_dword s35, s[24:25], 0x2000
	s_load_dword s36, s[24:25], 0x4000
	s_load_dword s37, s[24:25], 0x6000
	s_load_dword s38, s[24:25], 0x8000
	s_load_dword s39, s[24:25], 0xa000
	s_load_dword s40, s[24:25], 0xc000
	s_load_dword s41, s[24:25], 0xe000
	v_lshlrev_b32_e32 v5, 2, v4
	global_load_dword v5, v5, s[70:71] offset:96
	v_lshlrev_b32_e32 v6, 3, v4
	v_lshrrev_b32_e32 v7, 1, v4
	v_lshlrev_b32_e32 v7, 3, v7
	s_lshl_b32 s11, s10, 9
	s_add_u32 s26, s90, s11
	s_addc_u32 s27, s91, 0
	s_add_u32 s26, s26, 0x7c00000
	s_addc_u32 s27, s27, 0
	s_lshl_b32 s11, s10, 8
	s_add_u32 s28, s90, s11
	s_addc_u32 s29, s91, 0
	s_add_u32 s28, s28, 0x8400000
	s_addc_u32 s29, s29, 0
	s_mov_b32 s42, 0x6dc9c883
	s_mov_b32 s43, 0x3fc45f30
	s_waitcnt vmcnt(0) lgkmcnt(0)
	v_cvt_f32_i32_e32 v16, s34
	v_mul_f32_e32 v16, v5, v16
	v_cvt_f64_f32_e32 v[16:17], v16
	v_mul_f64 v[12:13], v[16:17], s[42:43]
	v_rndne_f64_e32 v[12:13], v[12:13]
	v_fma_f64 v[16:17], v[16:17], s[42:43], -v[12:13]
	v_cvt_f32_f64_e32 v17, v[16:17]
	v_cos_f32_e32 v16, v17
	v_sin_f32_e32 v17, v17
	v_cvt_f32_i32_e32 v18, s35
	v_mul_f32_e32 v18, v5, v18
	v_cvt_f64_f32_e32 v[18:19], v18
	v_mul_f64 v[12:13], v[18:19], s[42:43]
	v_rndne_f64_e32 v[12:13], v[12:13]
	v_fma_f64 v[18:19], v[18:19], s[42:43], -v[12:13]
	v_cvt_f32_f64_e32 v19, v[18:19]
	v_cos_f32_e32 v18, v19
	v_sin_f32_e32 v19, v19
	v_cvt_f32_i32_e32 v20, s36
	v_mul_f32_e32 v20, v5, v20
	v_cvt_f64_f32_e32 v[20:21], v20
	v_mul_f64 v[12:13], v[20:21], s[42:43]
	v_rndne_f64_e32 v[12:13], v[12:13]
	v_fma_f64 v[20:21], v[20:21], s[42:43], -v[12:13]
	v_cvt_f32_f64_e32 v21, v[20:21]
	v_cos_f32_e32 v20, v21
	v_sin_f32_e32 v21, v21
	v_cvt_f32_i32_e32 v22, s37
	v_mul_f32_e32 v22, v5, v22
	v_cvt_f64_f32_e32 v[22:23], v22
	v_mul_f64 v[12:13], v[22:23], s[42:43]
	v_rndne_f64_e32 v[12:13], v[12:13]
	v_fma_f64 v[22:23], v[22:23], s[42:43], -v[12:13]
	v_cvt_f32_f64_e32 v23, v[22:23]
	v_cos_f32_e32 v22, v23
	v_sin_f32_e32 v23, v23
	v_cvt_f32_i32_e32 v24, s38
	v_mul_f32_e32 v24, v5, v24
	v_cvt_f64_f32_e32 v[24:25], v24
	v_mul_f64 v[12:13], v[24:25], s[42:43]
	v_rndne_f64_e32 v[12:13], v[12:13]
	v_fma_f64 v[24:25], v[24:25], s[42:43], -v[12:13]
	v_cvt_f32_f64_e32 v25, v[24:25]
	v_cos_f32_e32 v24, v25
	v_sin_f32_e32 v25, v25
	v_cvt_f32_i32_e32 v26, s39
	v_mul_f32_e32 v26, v5, v26
	v_cvt_f64_f32_e32 v[26:27], v26
	v_mul_f64 v[12:13], v[26:27], s[42:43]
	v_rndne_f64_e32 v[12:13], v[12:13]
	v_fma_f64 v[26:27], v[26:27], s[42:43], -v[12:13]
	v_cvt_f32_f64_e32 v27, v[26:27]
	v_cos_f32_e32 v26, v27
	v_sin_f32_e32 v27, v27
	v_cvt_f32_i32_e32 v28, s40
	v_mul_f32_e32 v28, v5, v28
	v_cvt_f64_f32_e32 v[28:29], v28
	v_mul_f64 v[12:13], v[28:29], s[42:43]
	v_rndne_f64_e32 v[12:13], v[12:13]
	v_fma_f64 v[28:29], v[28:29], s[42:43], -v[12:13]
	v_cvt_f32_f64_e32 v29, v[28:29]
	v_cos_f32_e32 v28, v29
	v_sin_f32_e32 v29, v29
	v_cvt_f32_i32_e32 v30, s41
	v_mul_f32_e32 v30, v5, v30
	v_cvt_f64_f32_e32 v[30:31], v30
	v_mul_f64 v[12:13], v[30:31], s[42:43]
	v_rndne_f64_e32 v[12:13], v[12:13]
	v_fma_f64 v[30:31], v[30:31], s[42:43], -v[12:13]
	v_cvt_f32_f64_e32 v31, v[30:31]
	v_cos_f32_e32 v30, v31
	v_sin_f32_e32 v31, v31
	s_nop 1
	global_store_dwordx2 v6, v[16:17], s[26:27]
	s_add_u32 s26, s26, 0x100000
	s_addc_u32 s27, s27, 0
	global_store_dwordx2 v6, v[18:19], s[26:27]
	s_add_u32 s26, s26, 0x100000
	s_addc_u32 s27, s27, 0
	global_store_dwordx2 v6, v[20:21], s[26:27]
	s_add_u32 s26, s26, 0x100000
	s_addc_u32 s27, s27, 0
	global_store_dwordx2 v6, v[22:23], s[26:27]
	s_add_u32 s26, s26, 0x100000
	s_addc_u32 s27, s27, 0
	global_store_dwordx2 v6, v[24:25], s[26:27]
	s_add_u32 s26, s26, 0x100000
	s_addc_u32 s27, s27, 0
	global_store_dwordx2 v6, v[26:27], s[26:27]
	s_add_u32 s26, s26, 0x100000
	s_addc_u32 s27, s27, 0
	global_store_dwordx2 v6, v[28:29], s[26:27]
	s_add_u32 s26, s26, 0x100000
	s_addc_u32 s27, s27, 0
	global_store_dwordx2 v6, v[30:31], s[26:27]
	s_mov_b32 exec_lo, 0x55555555
	s_mov_b32 exec_hi, 0x55555555
	s_nop 1
	global_store_dwordx2 v7, v[16:17], s[28:29]
	s_add_u32 s28, s28, 0x80000
	s_addc_u32 s29, s29, 0
	global_store_dwordx2 v7, v[18:19], s[28:29]
	s_add_u32 s28, s28, 0x80000
	s_addc_u32 s29, s29, 0
	global_store_dwordx2 v7, v[20:21], s[28:29]
	s_add_u32 s28, s28, 0x80000
	s_addc_u32 s29, s29, 0
	global_store_dwordx2 v7, v[22:23], s[28:29]
	s_add_u32 s28, s28, 0x80000
	s_addc_u32 s29, s29, 0
	global_store_dwordx2 v7, v[24:25], s[28:29]
	s_add_u32 s28, s28, 0x80000
	s_addc_u32 s29, s29, 0
	global_store_dwordx2 v7, v[26:27], s[28:29]
	s_add_u32 s28, s28, 0x80000
	s_addc_u32 s29, s29, 0
	global_store_dwordx2 v7, v[28:29], s[28:29]
	s_add_u32 s28, s28, 0x80000
	s_addc_u32 s29, s29, 0
	global_store_dwordx2 v7, v[30:31], s[28:29]
	s_mov_b64 exec, -1
	s_nop 1
	v_and_b32_e32 v12, 7, v4
	v_lshrrev_b32_e32 v13, 3, v4
	v_lshlrev_b32_e32 v14, 4, v12
	s_mov_b32 s10, 0x5a000
	v_mul_lo_u32 v15, v13, s10
	v_add_u32_e32 v162, v15, v14
	v_add_u32_e32 v163, 0xb400, v162
	v_add_u32_e32 v164, 0x16800, v162
	v_add_u32_e32 v165, 0x21c00, v162
	v_add_u32_e32 v166, 0x2d000, v162
	v_add_u32_e32 v167, 0x38400, v162
	v_add_u32_e32 v168, 0x43800, v162
	v_add_u32_e32 v169, 0x4ec00, v162
	v_lshlrev_b32_e32 v14, 14, v12
	v_lshl_add_u32 v170, v13, 3, v14
	v_add_u32_e32 v171, 0x1000, v170
	v_add_u32_e32 v172, 0x2000, v170
	v_add_u32_e32 v173, 0x3000, v170
	s_mov_b32 s44, 0x42800000
	s_mov_b32 s45, 0x42800000
	s_lshr_b32 s10, s33, 6
	s_lshl_b32 s11, s2, 3
	s_add_u32 s46, s10, s11
	s_add_u32 s64, s90, 0x4000000
	s_addc_u32 s65, s91, 0
	s_cmpk_ge_u32 s46, 0x680
	s_cbranch_scc1 .Lp0c_four
; #define LAS __attribute__((address_space(3)))
; __host__ __device__ __forceinline__ int tile_mode(int pn) { return (pn <= 4) ? 1 : (pn >= 9 && pn <= 20) ? 2 : 0; }
; __host__ __device__ __forceinline__ int gemm_col_to_orig(int nprime) {
;     const int pn = nprime >> 8, xp = nprime & 255, bj = xp >> 7, x = xp & 127, md = tile_mode(pn);
;     if (md == 1) return 256 * pn + 64 * (x >> 5) + (x & 31) + 32 * bj;
;     if (md == 2) return 256 * pn + 128 * (x >> 6) + (x & 63) + 64 * bj;
;     return nprime;
; }
; __device__ __forceinline__ void transpose_item_fp8(const float* W, int N, unsigned char* W8, int pitch, int kofs, int k0, int n_src, int n_dst, float scale, LAS float* scr, int lane) {
;     const int r8 = lane >> 3, c4 = lane & 7;
;     f32x4 v[8];
; #pragma unroll
;     for (int i = 0; i < 8; ++i) v[i] = *(const f32x4*)(W + (size_t)(k0 + r8 + 8 * i) * N + n_src + 4 * c4);
; #pragma unroll
;     for (int i = 0; i < 8; ++i) { LAS float* d = scr + (r8 + 8 * i) * 33 + 4 * c4; d[0] = v[i][0]; d[1] = v[i][1]; d[2] = v[i][2]; d[3] = v[i][3]; }
;     asm volatile("s_waitcnt lgkmcnt(0)" ::: "memory");
;     const int n = lane & 31, cp = lane >> 5;
; #pragma unroll
;     for (int q = 0; q < 2; ++q) { const int ck = (2 * cp + q) * 16; const LAS float* sp = scr + ck * 33 + n; u32x4 o;
; #pragma unroll
;         for (int w = 0; w < 4; ++w) o[w] = pack_fp8x4(sp[(4 * w) * 33] * scale, sp[(4 * w + 1) * 33] * scale, sp[(4 * w + 2) * 33] * scale, sp[(4 * w + 3) * 33] * scale);
;         *(u32x4*)(W8 + (size_t)(n_dst + n) * pitch + kofs + k0 + ck) = o; }
	s_add_u32 s47, s46, 0x0
	s_mul_hi_u32 s48, s47, 0xb60b61
	s_mul_i32 s49, s48, 0x168
	s_sub_u32 s49, s47, s49
	s_lshl_b32 s50, s48, 1
	s_lshr_b32 s51, s49, 3
	s_and_b32 s52, s49, 7
	s_and_b32 s53, s52, 3
	s_lshr_b32 s54, s52, 2
	s_lshl_b32 s55, s53, 6
	s_lshl_b32 s56, s54, 5
	s_add_u32 s55, s55, s56
	s_bfe_u32 s56, s52, 0x10001
	s_lshl_b32 s56, s56, 7
	s_and_b32 s57, s52, 1
	s_lshl_b32 s57, s57, 5
	s_add_u32 s56, s56, s57
	s_lshl_b32 s57, s54, 6
	s_add_u32 s56, s56, s57
	s_lshl_b32 s57, s52, 5
	s_sub_u32 s58, s51, 9
	s_cmp_lt_u32 s58, 12
	s_cselect_b32 s57, s56, s57
	s_cmp_lt_u32 s51, 5
	s_cselect_b32 s57, s55, s57
	s_lshl_b32 s58, s51, 8
	s_add_u32 s57, s57, s58
	s_mul_i32 s58, s50, 0x2d0000
	s_lshl_b32 s57, s57, 2
	s_add_u32 s58, s58, s57
	s_add_u32 s60, s22, s58
	s_addc_u32 s61, s23, 0
	s_lshl_b32 s58, s49, 17
	s_lshl_b32 s59, s50, 6
	s_add_u32 s58, s58, s59
	s_add_u32 s74, s64, s58
	s_addc_u32 s75, s65, 0
	global_load_dwordx4 v[64:67], v162, s[60:61]
	global_load_dwordx4 v[68:71], v163, s[60:61]
	global_load_dwordx4 v[72:75], v164, s[60:61]
	global_load_dwordx4 v[76:79], v165, s[60:61]
	global_load_dwordx4 v[80:83], v166, s[60:61]
	global_load_dwordx4 v[84:87], v167, s[60:61]
	global_load_dwordx4 v[88:91], v168, s[60:61]
	global_load_dwordx4 v[92:95], v169, s[60:61]
	s_add_u32 s47, s46, 0x0
	s_mul_hi_u32 s48, s47, 0xb60b61
	s_mul_i32 s49, s48, 0x168
	s_sub_u32 s49, s47, s49
	s_lshl_b32 s50, s48, 1
	s_or_b32 s50, s50, 1
	s_lshr_b32 s51, s49, 3
	s_and_b32 s52, s49, 7
	s_and_b32 s53, s52, 3
	s_lshr_b32 s54, s52, 2
	s_lshl_b32 s55, s53, 6
	s_lshl_b32 s56, s54, 5
	s_add_u32 s55, s55, s56
	s_bfe_u32 s56, s52, 0x10001
	s_lshl_b32 s56, s56, 7
	s_and_b32 s57, s52, 1
	s_lshl_b32 s57, s57, 5
	s_add_u32 s56, s56, s57
	s_lshl_b32 s57, s54, 6
	s_add_u32 s56, s56, s57
	s_lshl_b32 s57, s52, 5
	s_sub_u32 s58, s51, 9
	s_cmp_lt_u32 s58, 12
	s_cselect_b32 s57, s56, s57
	s_cmp_lt_u32 s51, 5
	s_cselect_b32 s57, s55, s57
	s_lshl_b32 s58, s51, 8
	s_add_u32 s57, s57, s58
	s_mul_i32 s58, s50, 0x2d0000
	s_lshl_b32 s57, s57, 2
	s_add_u32 s58, s58, s57
	s_add_u32 s60, s22, s58
	s_addc_u32 s61, s23, 0
	s_lshl_b32 s58, s49, 17
	s_lshl_b32 s59, s50, 6
	s_add_u32 s58, s58, s59
	s_add_u32 s76, s64, s58
	s_addc_u32 s77, s65, 0
	global_load_dwordx4 v[96:99], v162, s[60:61]
	global_load_dwordx4 v[100:103], v163, s[60:61]
	global_load_dwordx4 v[104:107], v164, s[60:61]
	global_load_dwordx4 v[108:111], v165, s[60:61]
	global_load_dwordx4 v[112:115], v166, s[60:61]
	global_load_dwordx4 v[116:119], v167, s[60:61]
	global_load_dwordx4 v[120:123], v168, s[60:61]
	global_load_dwordx4 v[124:127], v169, s[60:61]
	s_add_u32 s47, s46, 0x800
	s_mul_hi_u32 s48, s47, 0xb60b61
	s_mul_i32 s49, s48, 0x168
	s_sub_u32 s49, s47, s49
	s_lshl_b32 s50, s48, 1
	s_lshr_b32 s51, s49, 3
	s_and_b32 s52, s49, 7
	s_and_b32 s53, s52, 3
	s_lshr_b32 s54, s52, 2
	s_lshl_b32 s55, s53, 6
	s_lshl_b32 s56, s54, 5
	s_add_u32 s55, s55, s56
	s_bfe_u32 s56, s52, 0x10001
	s_lshl_b32 s56, s56, 7
	s_and_b32 s57, s52, 1
	s_lshl_b32 s57, s57, 5
	s_add_u32 s56, s56, s57
	s_lshl_b32 s57, s54, 6
	s_add_u32 s56, s56, s57
	s_lshl_b32 s57, s52, 5
	s_sub_u32 s58, s51, 9
	s_cmp_lt_u32 s58, 12
	s_cselect_b32 s57, s56, s57
	s_cmp_lt_u32 s51, 5
	s_cselect_b32 s57, s55, s57
	s_lshl_b32 s58, s51, 8
	s_add_u32 s57, s57, s58
	s_mul_i32 s58, s50, 0x2d0000
	s_lshl_b32 s57, s57, 2
	s_add_u32 s58, s58, s57
	s_add_u32 s60, s22, s58
	s_addc_u32 s61, s23, 0
	s_lshl_b32 s58, s49, 17
	s_lshl_b32 s59, s50, 6
	s_add_u32 s58, s58, s59
	s_add_u32 s78, s64, s58
	s_addc_u32 s79, s65, 0
	global_load_dwordx4 v[128:131], v162, s[60:61]
	global_load_dwordx4 v[132:135], v163, s[60:61]
	global_load_dwordx4 v[136:139], v164, s[60:61]
	global_load_dwordx4 v[140:143], v165, s[60:61]
	global_load_dwordx4 v[144:147], v166, s[60:61]
	global_load_dwordx4 v[148:151], v167, s[60:61]
	global_load_dwordx4 v[152:155], v168, s[60:61]
	global_load_dwordx4 v[156:159], v169, s[60:61]
	s_waitcnt vmcnt(16)
	v_pk_mul_f32 v[64:65], v[64:65], s[44:45]
	v_pk_mul_f32 v[66:67], v[66:67], s[44:45]
	v_pk_mul_f32 v[68:69], v[68:69], s[44:45]
	v_pk_mul_f32 v[70:71], v[70:71], s[44:45]
	v_pk_mul_f32 v[72:73], v[72:73], s[44:45]
	v_pk_mul_f32 v[74:75], v[74:75], s[44:45]
	v_pk_mul_f32 v[76:77], v[76:77], s[44:45]
	v_pk_mul_f32 v[78:79], v[78:79], s[44:45]
	v_pk_mul_f32 v[80:81], v[80:81], s[44:45]
	v_pk_mul_f32 v[82:83], v[82:83], s[44:45]
	v_pk_mul_f32 v[84:85], v[84:85], s[44:45]
	v_pk_mul_f32 v[86:87], v[86:87], s[44:45]
	v_pk_mul_f32 v[88:89], v[88:89], s[44:45]
	v_pk_mul_f32 v[90:91], v[90:91], s[44:45]
	v_pk_mul_f32 v[92:93], v[92:93], s[44:45]
	v_pk_mul_f32 v[94:95], v[94:95], s[44:45]
	v_cvt_pk_fp8_f32 v8, v64, v68
	v_cvt_pk_fp8_f32 v9, v72, v76
	v_cvt_pk_fp8_f32 v10, v80, v84
	v_cvt_pk_fp8_f32 v11, v88, v92
	v_and_b32_e32 v8, 0xffff, v8
	v_and_b32_e32 v10, 0xffff, v10
	v_lshl_or_b32 v176, v9, 16, v8
	v_lshl_or_b32 v177, v11, 16, v10
	global_store_dwordx2 v170, v[176:177], s[74:75]
	v_cvt_pk_fp8_f32 v8, v65, v69
	v_cvt_pk_fp8_f32 v9, v73, v77
	v_cvt_pk_fp8_f32 v10, v81, v85
	v_cvt_pk_fp8_f32 v11, v89, v93
	v_and_b32_e32 v8, 0xffff, v8
	v_and_b32_e32 v10, 0xffff, v10
	v_lshl_or_b32 v178, v9, 16, v8
	v_lshl_or_b32 v179, v11, 16, v10
	global_store_dwordx2 v171, v[178:179], s[74:75]
	v_cvt_pk_fp8_f32 v8, v66, v70
	v_cvt_pk_fp8_f32 v9, v74, v78
	v_cvt_pk_fp8_f32 v10, v82, v86
	v_cvt_pk_fp8_f32 v11, v90, v94
	v_and_b32_e32 v8, 0xffff, v8
	v_and_b32_e32 v10, 0xffff, v10
	v_lshl_or_b32 v180, v9, 16, v8
	v_lshl_or_b32 v181, v11, 16, v10
	global_store_dwordx2 v172, v[180:181], s[74:75]
	v_cvt_pk_fp8_f32 v8, v67, v71
	v_cvt_pk_fp8_f32 v9, v75, v79
	v_cvt_pk_fp8_f32 v10, v83, v87
; #define LAS __attribute__((address_space(3)))
; __host__ __device__ __forceinline__ int tile_mode(int pn) { return (pn <= 4) ? 1 : (pn >= 9 && pn <= 20) ? 2 : 0; }
; __host__ __device__ __forceinline__ int gemm_col_to_orig(int nprime) {
;     const int pn = nprime >> 8, xp = nprime & 255, bj = xp >> 7, x = xp & 127, md = tile_mode(pn);
;     if (md == 1) return 256 * pn + 64 * (x >> 5) + (x & 31) + 32 * bj;
;     if (md == 2) return 256 * pn + 128 * (x >> 6) + (x & 63) + 64 * bj;
;     return nprime;
; }
; __device__ __forceinline__ void transpose_item_fp8(const float* W, int N, unsigned char* W8, int pitch, int kofs, int k0, int n_src, int n_dst, float scale, LAS float* scr, int lane) {
;     const int r8 = lane >> 3, c4 = lane & 7;
;     f32x4 v[8];
; #pragma unroll
;     for (int i = 0; i < 8; ++i) v[i] = *(const f32x4*)(W + (size_t)(k0 + r8 + 8 * i) * N + n_src + 4 * c4);
; #pragma unroll
;     for (int i = 0; i < 8; ++i) { LAS float* d = scr + (r8 + 8 * i) * 33 + 4 * c4; d[0] = v[i][0]; d[1] = v[i][1]; d[2] = v[i][2]; d[3] = v[i][3]; }
;     asm volatile("s_waitcnt lgkmcnt(0)" ::: "memory");
;     const int n = lane & 31, cp = lane >> 5;
; #pragma unroll
;     for (int q = 0; q < 2; ++q) { const int ck = (2 * cp + q) * 16; const LAS float* sp = scr + ck * 33 + n; u32x4 o;
; #pragma unroll
;         for (int w = 0; w < 4; ++w) o[w] = pack_fp8x4(sp[(4 * w) * 33] * scale, sp[(4 * w + 1) * 33] * scale, sp[(4 * w + 2) * 33] * scale, sp[(4 * w + 3) * 33] * scale);
;         *(u32x4*)(W8 + (size_t)(n_dst + n) * pitch + kofs + k0 + ck) = o; }
	v_cvt_pk_fp8_f32 v11, v91, v95
	v_and_b32_e32 v8, 0xffff, v8
	v_and_b32_e32 v10, 0xffff, v10
	v_lshl_or_b32 v182, v9, 16, v8
	v_lshl_or_b32 v183, v11, 16, v10
	global_store_dwordx2 v173, v[182:183], s[74:75]
	s_add_u32 s47, s46, 0x800
	s_mul_hi_u32 s48, s47, 0xb60b61
	s_mul_i32 s49, s48, 0x168
	s_sub_u32 s49, s47, s49
	s_lshl_b32 s50, s48, 1
	s_or_b32 s50, s50, 1
	s_lshr_b32 s51, s49, 3
	s_and_b32 s52, s49, 7
	s_and_b32 s53, s52, 3
	s_lshr_b32 s54, s52, 2
	s_lshl_b32 s55, s53, 6
	s_lshl_b32 s56, s54, 5
	s_add_u32 s55, s55, s56
	s_bfe_u32 s56, s52, 0x10001
	s_lshl_b32 s56, s56, 7
	s_and_b32 s57, s52, 1
	s_lshl_b32 s57, s57, 5
	s_add_u32 s56, s56, s57
	s_lshl_b32 s57, s54, 6
	s_add_u32 s56, s56, s57
	s_lshl_b32 s57, s52, 5
	s_sub_u32 s58, s51, 9
	s_cmp_lt_u32 s58, 12
	s_cselect_b32 s57, s56, s57
	s_cmp_lt_u32 s51, 5
	s_cselect_b32 s57, s55, s57
	s_lshl_b32 s58, s51, 8
	s_add_u32 s57, s57, s58
	s_mul_i32 s58, s50, 0x2d0000
	s_lshl_b32 s57, s57, 2
	s_add_u32 s58, s58, s57
	s_add_u32 s60, s22, s58
	s_addc_u32 s61, s23, 0
	s_lshl_b32 s58, s49, 17
	s_lshl_b32 s59, s50, 6
	s_add_u32 s58, s58, s59
	s_add_u32 s74, s64, s58
	s_addc_u32 s75, s65, 0
	global_load_dwordx4 v[64:67], v162, s[60:61]
	global_load_dwordx4 v[68:71], v163, s[60:61]
	global_load_dwordx4 v[72:75], v164, s[60:61]
	global_load_dwordx4 v[76:79], v165, s[60:61]
	global_load_dwordx4 v[80:83], v166, s[60:61]
	global_load_dwordx4 v[84:87], v167, s[60:61]
	global_load_dwordx4 v[88:91], v168, s[60:61]
	global_load_dwordx4 v[92:95], v169, s[60:61]
	s_waitcnt vmcnt(20)
	v_pk_mul_f32 v[96:97], v[96:97], s[44:45]
	v_pk_mul_f32 v[98:99], v[98:99], s[44:45]
	v_pk_mul_f32 v[100:101], v[100:101], s[44:45]
	v_pk_mul_f32 v[102:103], v[102:103], s[44:45]
	v_pk_mul_f32 v[104:105], v[104:105], s[44:45]
	v_pk_mul_f32 v[106:107], v[106:107], s[44:45]
	v_pk_mul_f32 v[108:109], v[108:109], s[44:45]
	v_pk_mul_f32 v[110:111], v[110:111], s[44:45]
	v_pk_mul_f32 v[112:113], v[112:113], s[44:45]
	v_pk_mul_f32 v[114:115], v[114:115], s[44:45]
	v_pk_mul_f32 v[116:117], v[116:117], s[44:45]
	v_pk_mul_f32 v[118:119], v[118:119], s[44:45]
	v_pk_mul_f32 v[120:121], v[120:121], s[44:45]
	v_pk_mul_f32 v[122:123], v[122:123], s[44:45]
	v_pk_mul_f32 v[124:125], v[124:125], s[44:45]
	v_pk_mul_f32 v[126:127], v[126:127], s[44:45]
	v_cvt_pk_fp8_f32 v8, v96, v100
	v_cvt_pk_fp8_f32 v9, v104, v108
	v_cvt_pk_fp8_f32 v10, v112, v116
	v_cvt_pk_fp8_f32 v11, v120, v124
	v_and_b32_e32 v8, 0xffff, v8
	v_and_b32_e32 v10, 0xffff, v10
	v_lshl_or_b32 v184, v9, 16, v8
	v_lshl_or_b32 v185, v11, 16, v10
	global_store_dwordx2 v170, v[184:185], s[76:77]
	v_cvt_pk_fp8_f32 v8, v97, v101
	v_cvt_pk_fp8_f32 v9, v105, v109
	v_cvt_pk_fp8_f32 v10, v113, v117
	v_cvt_pk_fp8_f32 v11, v121, v125
	v_and_b32_e32 v8, 0xffff, v8
	v_and_b32_e32 v10, 0xffff, v10
	v_lshl_or_b32 v186, v9, 16, v8
	v_lshl_or_b32 v187, v11, 16, v10
	global_store_dwordx2 v171, v[186:187], s[76:77]
	v_cvt_pk_fp8_f32 v8, v98, v102
	v_cvt_pk_fp8_f32 v9, v106, v110
	v_cvt_pk_fp8_f32 v10, v114, v118
	v_cvt_pk_fp8_f32 v11, v122, v126
	v_and_b32_e32 v8, 0xffff, v8
	v_and_b32_e32 v10, 0xffff, v10
	v_lshl_or_b32 v188, v9, 16, v8
	v_lshl_or_b32 v189, v11, 16, v10
	global_store_dwordx2 v172, v[188:189], s[76:77]
	v_cvt_pk_fp8_f32 v8, v99, v103
	v_cvt_pk_fp8_f32 v9, v107, v111
	v_cvt_pk_fp8_f32 v10, v115, v119
	v_cvt_pk_fp8_f32 v11, v123, v127
	v_and_b32_e32 v8, 0xffff, v8
	v_and_b32_e32 v10, 0xffff, v10
	v_lshl_or_b32 v190, v9, 16, v8
	v_lshl_or_b32 v191, v11, 16, v10
	global_store_dwordx2 v173, v[190:191], s[76:77]
	s_add_u32 s47, s46, 0x1000
	s_mul_hi_u32 s48, s47, 0xb60b61
	s_mul_i32 s49, s48, 0x168
	s_sub_u32 s49, s47, s49
	s_lshl_b32 s50, s48, 1
	s_lshr_b32 s51, s49, 3
	s_and_b32 s52, s49, 7
	s_and_b32 s53, s52, 3
	s_lshr_b32 s54, s52, 2
	s_lshl_b32 s55, s53, 6
	s_lshl_b32 s56, s54, 5
	s_add_u32 s55, s55, s56
	s_bfe_u32 s56, s52, 0x10001
	s_lshl_b32 s56, s56, 7
	s_and_b32 s57, s52, 1
	s_lshl_b32 s57, s57, 5
	s_add_u32 s56, s56, s57
	s_lshl_b32 s57, s54, 6
	s_add_u32 s56, s56, s57
	s_lshl_b32 s57, s52, 5
	s_sub_u32 s58, s51, 9
	s_cmp_lt_u32 s58, 12
	s_cselect_b32 s57, s56, s57
	s_cmp_lt_u32 s51, 5
	s_cselect_b32 s57, s55, s57
	s_lshl_b32 s58, s51, 8
	s_add_u32 s57, s57, s58
	s_mul_i32 s58, s50, 0x2d0000
	s_lshl_b32 s57, s57, 2
	s_add_u32 s58, s58, s57
	s_add_u32 s60, s22, s58
	s_addc_u32 s61, s23, 0
	s_lshl_b32 s58, s49, 17
	s_lshl_b32 s59, s50, 6
	s_add_u32 s58, s58, s59
	s_add_u32 s76, s64, s58
	s_addc_u32 s77, s65, 0
	global_load_dwordx4 v[96:99], v162, s[60:61]
	global_load_dwordx4 v[100:103], v163, s[60:61]
	global_load_dwordx4 v[104:107], v164, s[60:61]
	global_load_dwordx4 v[108:111], v165, s[60:61]
	global_load_dwordx4 v[112:115], v166, s[60:61]
	global_load_dwordx4 v[116:119], v167, s[60:61]
	global_load_dwordx4 v[120:123], v168, s[60:61]
	global_load_dwordx4 v[124:127], v169, s[60:61]
	s_waitcnt vmcnt(24)
; #define LAS __attribute__((address_space(3)))
; __device__ __forceinline__ void transpose_item_fp8(const float* W, int N, unsigned char* W8, int pitch, int kofs, int k0, int n_src, int n_dst, float scale, LAS float* scr, int lane) {
;     const int r8 = lane >> 3, c4 = lane & 7;
;     f32x4 v[8];
; #pragma unroll
;     for (int i = 0; i < 8; ++i) v[i] = *(const f32x4*)(W + (size_t)(k0 + r8 + 8 * i) * N + n_src + 4 * c4);
; #pragma unroll
;     for (int i = 0; i < 8; ++i) { LAS float* d = scr + (r8 + 8 * i) * 33 + 4 * c4; d[0] = v[i][0]; d[1] = v[i][1]; d[2] = v[i][2]; d[3] = v[i][3]; }
;     asm volatile("s_waitcnt lgkmcnt(0)" ::: "memory");
;     const int n = lane & 31, cp = lane >> 5;
; #pragma unroll
;     for (int q = 0; q < 2; ++q) { const int ck = (2 * cp + q) * 16; const LAS float* sp = scr + ck * 33 + n; u32x4 o;
; #pragma unroll
;         for (int w = 0; w < 4; ++w) o[w] = pack_fp8x4(sp[(4 * w) * 33] * scale, sp[(4 * w + 1) * 33] * scale, sp[(4 * w + 2) * 33] * scale, sp[(4 * w + 3) * 33] * scale);
;         *(u32x4*)(W8 + (size_t)(n_dst + n) * pitch + kofs + k0 + ck) = o; }
	v_pk_mul_f32 v[128:129], v[128:129], s[44:45]
	v_pk_mul_f32 v[130:131], v[130:131], s[44:45]
	v_pk_mul_f32 v[132:133], v[132:133], s[44:45]
	v_pk_mul_f32 v[134:135], v[134:135], s[44:45]
	v_pk_mul_f32 v[136:137], v[136:137], s[44:45]
	v_pk_mul_f32 v[138:139], v[138:139], s[44:45]
	v_pk_mul_f32 v[140:141], v[140:141], s[44:45]
	v_pk_mul_f32 v[142:143], v[142:143], s[44:45]
	v_pk_mul_f32 v[144:145], v[144:145], s[44:45]
	v_pk_mul_f32 v[146:147], v[146:147], s[44:45]
	v_pk_mul_f32 v[148:149], v[148:149], s[44:45]
	v_pk_mul_f32 v[150:151], v[150:151], s[44:45]
	v_pk_mul_f32 v[152:153], v[152:153], s[44:45]
	v_pk_mul_f32 v[154:155], v[154:155], s[44:45]
	v_pk_mul_f32 v[156:157], v[156:157], s[44:45]
	v_pk_mul_f32 v[158:159], v[158:159], s[44:45]
	v_cvt_pk_fp8_f32 v8, v128, v132
	v_cvt_pk_fp8_f32 v9, v136, v140
	v_cvt_pk_fp8_f32 v10, v144, v148
	v_cvt_pk_fp8_f32 v11, v152, v156
	v_and_b32_e32 v8, 0xffff, v8
	v_and_b32_e32 v10, 0xffff, v10
	v_lshl_or_b32 v176, v9, 16, v8
	v_lshl_or_b32 v177, v11, 16, v10
	global_store_dwordx2 v170, v[176:177], s[78:79]
	v_cvt_pk_fp8_f32 v8, v129, v133
	v_cvt_pk_fp8_f32 v9, v137, v141
	v_cvt_pk_fp8_f32 v10, v145, v149
	v_cvt_pk_fp8_f32 v11, v153, v157
	v_and_b32_e32 v8, 0xffff, v8
	v_and_b32_e32 v10, 0xffff, v10
	v_lshl_or_b32 v178, v9, 16, v8
	v_lshl_or_b32 v179, v11, 16, v10
	global_store_dwordx2 v171, v[178:179], s[78:79]
	v_cvt_pk_fp8_f32 v8, v130, v134
	v_cvt_pk_fp8_f32 v9, v138, v142
	v_cvt_pk_fp8_f32 v10, v146, v150
	v_cvt_pk_fp8_f32 v11, v154, v158
	v_and_b32_e32 v8, 0xffff, v8
	v_and_b32_e32 v10, 0xffff, v10
	v_lshl_or_b32 v180, v9, 16, v8
	v_lshl_or_b32 v181, v11, 16, v10
	global_store_dwordx2 v172, v[180:181], s[78:79]
	v_cvt_pk_fp8_f32 v8, v131, v135
	v_cvt_pk_fp8_f32 v9, v139, v143
	v_cvt_pk_fp8_f32 v10, v147, v151
	v_cvt_pk_fp8_f32 v11, v155, v159
	v_and_b32_e32 v8, 0xffff, v8
	v_and_b32_e32 v10, 0xffff, v10
	v_lshl_or_b32 v182, v9, 16, v8
	v_lshl_or_b32 v183, v11, 16, v10
	global_store_dwordx2 v173, v[182:183], s[78:79]
	s_add_u32 s47, s46, 0x1000
	s_mul_hi_u32 s48, s47, 0xb60b61
	s_mul_i32 s49, s48, 0x168
	s_sub_u32 s49, s47, s49
	s_lshl_b32 s50, s48, 1
	s_or_b32 s50, s50, 1
	s_lshr_b32 s51, s49, 3
	s_and_b32 s52, s49, 7
	s_and_b32 s53, s52, 3
	s_lshr_b32 s54, s52, 2
	s_lshl_b32 s55, s53, 6
	s_lshl_b32 s56, s54, 5
	s_add_u32 s55, s55, s56
	s_bfe_u32 s56, s52, 0x10001
	s_lshl_b32 s56, s56, 7
	s_and_b32 s57, s52, 1
	s_lshl_b32 s57, s57, 5
	s_add_u32 s56, s56, s57
	s_lshl_b32 s57, s54, 6
	s_add_u32 s56, s56, s57
	s_lshl_b32 s57, s52, 5
	s_sub_u32 s58, s51, 9
	s_cmp_lt_u32 s58, 12
	s_cselect_b32 s57, s56, s57
	s_cmp_lt_u32 s51, 5
	s_cselect_b32 s57, s55, s57
	s_lshl_b32 s58, s51, 8
	s_add_u32 s57, s57, s58
	s_mul_i32 s58, s50, 0x2d0000
	s_lshl_b32 s57, s57, 2
	s_add_u32 s58, s58, s57
	s_add_u32 s60, s22, s58
	s_addc_u32 s61, s23, 0
	s_lshl_b32 s58, s49, 17
	s_lshl_b32 s59, s50, 6
	s_add_u32 s58, s58, s59
	s_add_u32 s78, s64, s58
	s_addc_u32 s79, s65, 0
	global_load_dwordx4 v[128:131], v162, s[60:61]
	global_load_dwordx4 v[132:135], v163, s[60:61]
	global_load_dwordx4 v[136:139], v164, s[60:61]
	global_load_dwordx4 v[140:143], v165, s[60:61]
	global_load_dwordx4 v[144:147], v166, s[60:61]
	global_load_dwordx4 v[148:151], v167, s[60:61]
	global_load_dwordx4 v[152:155], v168, s[60:61]
	global_load_dwordx4 v[156:159], v169, s[60:61]
	s_waitcnt vmcnt(24)
	v_pk_mul_f32 v[64:65], v[64:65], s[44:45]
	v_pk_mul_f32 v[66:67], v[66:67], s[44:45]
	v_pk_mul_f32 v[68:69], v[68:69], s[44:45]
	v_pk_mul_f32 v[70:71], v[70:71], s[44:45]
	v_pk_mul_f32 v[72:73], v[72:73], s[44:45]
	v_pk_mul_f32 v[74:75], v[74:75], s[44:45]
	v_pk_mul_f32 v[76:77], v[76:77], s[44:45]
	v_pk_mul_f32 v[78:79], v[78:79], s[44:45]
	v_pk_mul_f32 v[80:81], v[80:81], s[44:45]
	v_pk_mul_f32 v[82:83], v[82:83], s[44:45]
	v_pk_mul_f32 v[84:85], v[84:85], s[44:45]
	v_pk_mul_f32 v[86:87], v[86:87], s[44:45]
	v_pk_mul_f32 v[88:89], v[88:89], s[44:45]
	v_pk_mul_f32 v[90:91], v[90:91], s[44:45]
	v_pk_mul_f32 v[92:93], v[92:93], s[44:45]
	v_pk_mul_f32 v[94:95], v[94:95], s[44:45]
	v_cvt_pk_fp8_f32 v8, v64, v68
	v_cvt_pk_fp8_f32 v9, v72, v76
	v_cvt_pk_fp8_f32 v10, v80, v84
	v_cvt_pk_fp8_f32 v11, v88, v92
	v_and_b32_e32 v8, 0xffff, v8
	v_and_b32_e32 v10, 0xffff, v10
	v_lshl_or_b32 v184, v9, 16, v8
	v_lshl_or_b32 v185, v11, 16, v10
	global_store_dwordx2 v170, v[184:185], s[74:75]
	v_cvt_pk_fp8_f32 v8, v65, v69
	v_cvt_pk_fp8_f32 v9, v73, v77
	v_cvt_pk_fp8_f32 v10, v81, v85
	v_cvt_pk_fp8_f32 v11, v89, v93
	v_and_b32_e32 v8, 0xffff, v8
	v_and_b32_e32 v10, 0xffff, v10
	v_lshl_or_b32 v186, v9, 16, v8
	v_lshl_or_b32 v187, v11, 16, v10
	global_store_dwordx2 v171, v[186:187], s[74:75]
	v_cvt_pk_fp8_f32 v8, v66, v70
	v_cvt_pk_fp8_f32 v9, v74, v78
	v_cvt_pk_fp8_f32 v10, v82, v86
	v_cvt_pk_fp8_f32 v11, v90, v94
	v_and_b32_e32 v8, 0xffff, v8
	v_and_b32_e32 v10, 0xffff, v10
	v_lshl_or_b32 v188, v9, 16, v8
	v_lshl_or_b32 v189, v11, 16, v10
	global_store_dwordx2 v172, v[188:189], s[74:75]
	v_cvt_pk_fp8_f32 v8, v67, v71
	v_cvt_pk_fp8_f32 v9, v75, v79
	v_cvt_pk_fp8_f32 v10, v83, v87
	v_cvt_pk_fp8_f32 v11, v91, v95
	v_and_b32_e32 v8, 0xffff, v8
	v_and_b32_e32 v10, 0xffff, v10
	v_lshl_or_b32 v190, v9, 16, v8
	v_lshl_or_b32 v191, v11, 16, v10
	global_store_dwordx2 v173, v[190:191], s[74:75]
	s_waitcnt vmcnt(16)
; #define LAS __attribute__((address_space(3)))
; __host__ __device__ __forceinline__ int tile_mode(int pn) { return (pn <= 4) ? 1 : (pn >= 9 && pn <= 20) ? 2 : 0; }
; __host__ __device__ __forceinline__ int gemm_col_to_orig(int nprime) {
;     const int pn = nprime >> 8, xp = nprime & 255, bj = xp >> 7, x = xp & 127, md = tile_mode(pn);
;     if (md == 1) return 256 * pn + 64 * (x >> 5) + (x & 31) + 32 * bj;
;     if (md == 2) return 256 * pn + 128 * (x >> 6) + (x & 63) + 64 * bj;
;     return nprime;
; }
; __device__ __forceinline__ void transpose_item_fp8(const float* W, int N, unsigned char* W8, int pitch, int kofs, int k0, int n_src, int n_dst, float scale, LAS float* scr, int lane) {
;     const int r8 = lane >> 3, c4 = lane & 7;
;     f32x4 v[8];
; #pragma unroll
;     for (int i = 0; i < 8; ++i) v[i] = *(const f32x4*)(W + (size_t)(k0 + r8 + 8 * i) * N + n_src + 4 * c4);
; #pragma unroll
;     for (int i = 0; i < 8; ++i) { LAS float* d = scr + (r8 + 8 * i) * 33 + 4 * c4; d[0] = v[i][0]; d[1] = v[i][1]; d[2] = v[i][2]; d[3] = v[i][3]; }
;     asm volatile("s_waitcnt lgkmcnt(0)" ::: "memory");
;     const int n = lane & 31, cp = lane >> 5;
; #pragma unroll
;     for (int q = 0; q < 2; ++q) { const int ck = (2 * cp + q) * 16; const LAS float* sp = scr + ck * 33 + n; u32x4 o;
; #pragma unroll
;         for (int w = 0; w < 4; ++w) o[w] = pack_fp8x4(sp[(4 * w) * 33] * scale, sp[(4 * w + 1) * 33] * scale, sp[(4 * w + 2) * 33] * scale, sp[(4 * w + 3) * 33] * scale);
;         *(u32x4*)(W8 + (size_t)(n_dst + n) * pitch + kofs + k0 + ck) = o; }
	v_pk_mul_f32 v[96:97], v[96:97], s[44:45]
	v_pk_mul_f32 v[98:99], v[98:99], s[44:45]
	v_pk_mul_f32 v[100:101], v[100:101], s[44:45]
	v_pk_mul_f32 v[102:103], v[102:103], s[44:45]
	v_pk_mul_f32 v[104:105], v[104:105], s[44:45]
	v_pk_mul_f32 v[106:107], v[106:107], s[44:45]
	v_pk_mul_f32 v[108:109], v[108:109], s[44:45]
	v_pk_mul_f32 v[110:111], v[110:111], s[44:45]
	v_pk_mul_f32 v[112:113], v[112:113], s[44:45]
	v_pk_mul_f32 v[114:115], v[114:115], s[44:45]
	v_pk_mul_f32 v[116:117], v[116:117], s[44:45]
	v_pk_mul_f32 v[118:119], v[118:119], s[44:45]
	v_pk_mul_f32 v[120:121], v[120:121], s[44:45]
	v_pk_mul_f32 v[122:123], v[122:123], s[44:45]
	v_pk_mul_f32 v[124:125], v[124:125], s[44:45]
	v_pk_mul_f32 v[126:127], v[126:127], s[44:45]
	v_cvt_pk_fp8_f32 v8, v96, v100
	v_cvt_pk_fp8_f32 v9, v104, v108
	v_cvt_pk_fp8_f32 v10, v112, v116
	v_cvt_pk_fp8_f32 v11, v120, v124
	v_and_b32_e32 v8, 0xffff, v8
	v_and_b32_e32 v10, 0xffff, v10
	v_lshl_or_b32 v176, v9, 16, v8
	v_lshl_or_b32 v177, v11, 16, v10
	global_store_dwordx2 v170, v[176:177], s[76:77]
	v_cvt_pk_fp8_f32 v8, v97, v101
	v_cvt_pk_fp8_f32 v9, v105, v109
	v_cvt_pk_fp8_f32 v10, v113, v117
	v_cvt_pk_fp8_f32 v11, v121, v125
	v_and_b32_e32 v8, 0xffff, v8
	v_and_b32_e32 v10, 0xffff, v10
	v_lshl_or_b32 v178, v9, 16, v8
	v_lshl_or_b32 v179, v11, 16, v10
	global_store_dwordx2 v171, v[178:179], s[76:77]
	v_cvt_pk_fp8_f32 v8, v98, v102
	v_cvt_pk_fp8_f32 v9, v106, v110
	v_cvt_pk_fp8_f32 v10, v114, v118
	v_cvt_pk_fp8_f32 v11, v122, v126
	v_and_b32_e32 v8, 0xffff, v8
	v_and_b32_e32 v10, 0xffff, v10
	v_lshl_or_b32 v180, v9, 16, v8
	v_lshl_or_b32 v181, v11, 16, v10
	global_store_dwordx2 v172, v[180:181], s[76:77]
	v_cvt_pk_fp8_f32 v8, v99, v103
	v_cvt_pk_fp8_f32 v9, v107, v111
	v_cvt_pk_fp8_f32 v10, v115, v119
	v_cvt_pk_fp8_f32 v11, v123, v127
	v_and_b32_e32 v8, 0xffff, v8
	v_and_b32_e32 v10, 0xffff, v10
	v_lshl_or_b32 v182, v9, 16, v8
	v_lshl_or_b32 v183, v11, 16, v10
	global_store_dwordx2 v173, v[182:183], s[76:77]
	s_waitcnt vmcnt(8)
	v_pk_mul_f32 v[128:129], v[128:129], s[44:45]
	v_pk_mul_f32 v[130:131], v[130:131], s[44:45]
	v_pk_mul_f32 v[132:133], v[132:133], s[44:45]
	v_pk_mul_f32 v[134:135], v[134:135], s[44:45]
	v_pk_mul_f32 v[136:137], v[136:137], s[44:45]
	v_pk_mul_f32 v[138:139], v[138:139], s[44:45]
	v_pk_mul_f32 v[140:141], v[140:141], s[44:45]
	v_pk_mul_f32 v[142:143], v[142:143], s[44:45]
	v_pk_mul_f32 v[144:145], v[144:145], s[44:45]
	v_pk_mul_f32 v[146:147], v[146:147], s[44:45]
	v_pk_mul_f32 v[148:149], v[148:149], s[44:45]
	v_pk_mul_f32 v[150:151], v[150:151], s[44:45]
	v_pk_mul_f32 v[152:153], v[152:153], s[44:45]
	v_pk_mul_f32 v[154:155], v[154:155], s[44:45]
	v_pk_mul_f32 v[156:157], v[156:157], s[44:45]
	v_pk_mul_f32 v[158:159], v[158:159], s[44:45]
	v_cvt_pk_fp8_f32 v8, v128, v132
	v_cvt_pk_fp8_f32 v9, v136, v140
	v_cvt_pk_fp8_f32 v10, v144, v148
	v_cvt_pk_fp8_f32 v11, v152, v156
	v_and_b32_e32 v8, 0xffff, v8
	v_and_b32_e32 v10, 0xffff, v10
	v_lshl_or_b32 v184, v9, 16, v8
	v_lshl_or_b32 v185, v11, 16, v10
	global_store_dwordx2 v170, v[184:185], s[78:79]
	v_cvt_pk_fp8_f32 v8, v129, v133
	v_cvt_pk_fp8_f32 v9, v137, v141
	v_cvt_pk_fp8_f32 v10, v145, v149
	v_cvt_pk_fp8_f32 v11, v153, v157
	v_and_b32_e32 v8, 0xffff, v8
	v_and_b32_e32 v10, 0xffff, v10
	v_lshl_or_b32 v186, v9, 16, v8
	v_lshl_or_b32 v187, v11, 16, v10
	global_store_dwordx2 v171, v[186:187], s[78:79]
	v_cvt_pk_fp8_f32 v8, v130, v134
	v_cvt_pk_fp8_f32 v9, v138, v142
	v_cvt_pk_fp8_f32 v10, v146, v150
	v_cvt_pk_fp8_f32 v11, v154, v158
	v_and_b32_e32 v8, 0xffff, v8
	v_and_b32_e32 v10, 0xffff, v10
	v_lshl_or_b32 v188, v9, 16, v8
	v_lshl_or_b32 v189, v11, 16, v10
	global_store_dwordx2 v172, v[188:189], s[78:79]
	v_cvt_pk_fp8_f32 v8, v131, v135
	v_cvt_pk_fp8_f32 v9, v139, v143
	v_cvt_pk_fp8_f32 v10, v147, v151
	v_cvt_pk_fp8_f32 v11, v155, v159
	v_and_b32_e32 v8, 0xffff, v8
	v_and_b32_e32 v10, 0xffff, v10
	v_lshl_or_b32 v190, v9, 16, v8
	v_lshl_or_b32 v191, v11, 16, v10
	global_store_dwordx2 v173, v[190:191], s[78:79]
	s_branch .Lp0c_end
.Lp0c_four:
	s_add_u32 s47, s46, 0x0
	s_mul_hi_u32 s48, s47, 0xb60b61
	s_mul_i32 s49, s48, 0x168
	s_sub_u32 s49, s47, s49
	s_lshl_b32 s50, s48, 1
	s_lshr_b32 s51, s49, 3
	s_and_b32 s52, s49, 7
	s_and_b32 s53, s52, 3
	s_lshr_b32 s54, s52, 2
	s_lshl_b32 s55, s53, 6
	s_lshl_b32 s56, s54, 5
	s_add_u32 s55, s55, s56
	s_bfe_u32 s56, s52, 0x10001
	s_lshl_b32 s56, s56, 7
	s_and_b32 s57, s52, 1
	s_lshl_b32 s57, s57, 5
	s_add_u32 s56, s56, s57
	s_lshl_b32 s57, s54, 6
	s_add_u32 s56, s56, s57
	s_lshl_b32 s57, s52, 5
	s_sub_u32 s58, s51, 9
	s_cmp_lt_u32 s58, 12
	s_cselect_b32 s57, s56, s57
	s_cmp_lt_u32 s51, 5
	s_cselect_b32 s57, s55, s57
	s_lshl_b32 s58, s51, 8
	s_add_u32 s57, s57, s58
	s_mul_i32 s58, s50, 0x2d0000
	s_lshl_b32 s57, s57, 2
	s_add_u32 s58, s58, s57
	s_add_u32 s60, s22, s58
	s_addc_u32 s61, s23, 0
	s_lshl_b32 s58, s49, 17
	s_lshl_b32 s59, s50, 6
	s_add_u32 s58, s58, s59
	s_add_u32 s74, s64, s58
	s_addc_u32 s75, s65, 0
	global_load_dwordx4 v[64:67], v162, s[60:61]
	global_load_dwordx4 v[68:71], v163, s[60:61]
	global_load_dwordx4 v[72:75], v164, s[60:61]
	global_load_dwordx4 v[76:79], v165, s[60:61]
	global_load_dwordx4 v[80:83], v166, s[60:61]
	global_load_dwordx4 v[84:87], v167, s[60:61]
	global_load_dwordx4 v[88:91], v168, s[60:61]
	global_load_dwordx4 v[92:95], v169, s[60:61]
	s_add_u32 s47, s46, 0x0
	s_mul_hi_u32 s48, s47, 0xb60b61
	s_mul_i32 s49, s48, 0x168
	s_sub_u32 s49, s47, s49
	s_lshl_b32 s50, s48, 1
	s_or_b32 s50, s50, 1
	s_lshr_b32 s51, s49, 3
	s_and_b32 s52, s49, 7
	s_and_b32 s53, s52, 3
	s_lshr_b32 s54, s52, 2
	s_lshl_b32 s55, s53, 6
	s_lshl_b32 s56, s54, 5
	s_add_u32 s55, s55, s56
; #define LAS __attribute__((address_space(3)))
; __host__ __device__ __forceinline__ int tile_mode(int pn) { return (pn <= 4) ? 1 : (pn >= 9 && pn <= 20) ? 2 : 0; }
; __host__ __device__ __forceinline__ int gemm_col_to_orig(int nprime) {
;     const int pn = nprime >> 8, xp = nprime & 255, bj = xp >> 7, x = xp & 127, md = tile_mode(pn);
;     if (md == 1) return 256 * pn + 64 * (x >> 5) + (x & 31) + 32 * bj;
;     if (md == 2) return 256 * pn + 128 * (x >> 6) + (x & 63) + 64 * bj;
;     return nprime;
; }
; __device__ __forceinline__ void transpose_item_fp8(const float* W, int N, unsigned char* W8, int pitch, int kofs, int k0, int n_src, int n_dst, float scale, LAS float* scr, int lane) {
;     const int r8 = lane >> 3, c4 = lane & 7;
;     f32x4 v[8];
; #pragma unroll
;     for (int i = 0; i < 8; ++i) v[i] = *(const f32x4*)(W + (size_t)(k0 + r8 + 8 * i) * N + n_src + 4 * c4);
; #pragma unroll
;     for (int i = 0; i < 8; ++i) { LAS float* d = scr + (r8 + 8 * i) * 33 + 4 * c4; d[0] = v[i][0]; d[1] = v[i][1]; d[2] = v[i][2]; d[3] = v[i][3]; }
;     asm volatile("s_waitcnt lgkmcnt(0)" ::: "memory");
;     const int n = lane & 31, cp = lane >> 5;
; #pragma unroll
;     for (int q = 0; q < 2; ++q) { const int ck = (2 * cp + q) * 16; const LAS float* sp = scr + ck * 33 + n; u32x4 o;
; #pragma unroll
;         for (int w = 0; w < 4; ++w) o[w] = pack_fp8x4(sp[(4 * w) * 33] * scale, sp[(4 * w + 1) * 33] * scale, sp[(4 * w + 2) * 33] * scale, sp[(4 * w + 3) * 33] * scale);
;         *(u32x4*)(W8 + (size_t)(n_dst + n) * pitch + kofs + k0 + ck) = o; }
	s_bfe_u32 s56, s52, 0x10001
	s_lshl_b32 s56, s56, 7
	s_and_b32 s57, s52, 1
	s_lshl_b32 s57, s57, 5
	s_add_u32 s56, s56, s57
	s_lshl_b32 s57, s54, 6
	s_add_u32 s56, s56, s57
	s_lshl_b32 s57, s52, 5
	s_sub_u32 s58, s51, 9
	s_cmp_lt_u32 s58, 12
	s_cselect_b32 s57, s56, s57
	s_cmp_lt_u32 s51, 5
	s_cselect_b32 s57, s55, s57
	s_lshl_b32 s58, s51, 8
	s_add_u32 s57, s57, s58
	s_mul_i32 s58, s50, 0x2d0000
	s_lshl_b32 s57, s57, 2
	s_add_u32 s58, s58, s57
	s_add_u32 s60, s22, s58
	s_addc_u32 s61, s23, 0
	s_lshl_b32 s58, s49, 17
	s_lshl_b32 s59, s50, 6
	s_add_u32 s58, s58, s59
	s_add_u32 s76, s64, s58
	s_addc_u32 s77, s65, 0
	global_load_dwordx4 v[96:99], v162, s[60:61]
	global_load_dwordx4 v[100:103], v163, s[60:61]
	global_load_dwordx4 v[104:107], v164, s[60:61]
	global_load_dwordx4 v[108:111], v165, s[60:61]
	global_load_dwordx4 v[112:115], v166, s[60:61]
	global_load_dwordx4 v[116:119], v167, s[60:61]
	global_load_dwordx4 v[120:123], v168, s[60:61]
	global_load_dwordx4 v[124:127], v169, s[60:61]
	s_add_u32 s47, s46, 0x800
	s_mul_hi_u32 s48, s47, 0xb60b61
	s_mul_i32 s49, s48, 0x168
	s_sub_u32 s49, s47, s49
	s_lshl_b32 s50, s48, 1
	s_lshr_b32 s51, s49, 3
	s_and_b32 s52, s49, 7
	s_and_b32 s53, s52, 3
	s_lshr_b32 s54, s52, 2
	s_lshl_b32 s55, s53, 6
	s_lshl_b32 s56, s54, 5
	s_add_u32 s55, s55, s56
	s_bfe_u32 s56, s52, 0x10001
	s_lshl_b32 s56, s56, 7
	s_and_b32 s57, s52, 1
	s_lshl_b32 s57, s57, 5
	s_add_u32 s56, s56, s57
	s_lshl_b32 s57, s54, 6
	s_add_u32 s56, s56, s57
	s_lshl_b32 s57, s52, 5
	s_sub_u32 s58, s51, 9
	s_cmp_lt_u32 s58, 12
	s_cselect_b32 s57, s56, s57
	s_cmp_lt_u32 s51, 5
	s_cselect_b32 s57, s55, s57
	s_lshl_b32 s58, s51, 8
	s_add_u32 s57, s57, s58
	s_mul_i32 s58, s50, 0x2d0000
	s_lshl_b32 s57, s57, 2
	s_add_u32 s58, s58, s57
	s_add_u32 s60, s22, s58
	s_addc_u32 s61, s23, 0
	s_lshl_b32 s58, s49, 17
	s_lshl_b32 s59, s50, 6
	s_add_u32 s58, s58, s59
	s_add_u32 s78, s64, s58
	s_addc_u32 s79, s65, 0
	global_load_dwordx4 v[128:131], v162, s[60:61]
	global_load_dwordx4 v[132:135], v163, s[60:61]
	global_load_dwordx4 v[136:139], v164, s[60:61]
	global_load_dwordx4 v[140:143], v165, s[60:61]
	global_load_dwordx4 v[144:147], v166, s[60:61]
	global_load_dwordx4 v[148:151], v167, s[60:61]
	global_load_dwordx4 v[152:155], v168, s[60:61]
	global_load_dwordx4 v[156:159], v169, s[60:61]
	s_waitcnt vmcnt(16)
	v_pk_mul_f32 v[64:65], v[64:65], s[44:45]
	v_pk_mul_f32 v[66:67], v[66:67], s[44:45]
	v_pk_mul_f32 v[68:69], v[68:69], s[44:45]
	v_pk_mul_f32 v[70:71], v[70:71], s[44:45]
	v_pk_mul_f32 v[72:73], v[72:73], s[44:45]
	v_pk_mul_f32 v[74:75], v[74:75], s[44:45]
	v_pk_mul_f32 v[76:77], v[76:77], s[44:45]
	v_pk_mul_f32 v[78:79], v[78:79], s[44:45]
	v_pk_mul_f32 v[80:81], v[80:81], s[44:45]
	v_pk_mul_f32 v[82:83], v[82:83], s[44:45]
	v_pk_mul_f32 v[84:85], v[84:85], s[44:45]
	v_pk_mul_f32 v[86:87], v[86:87], s[44:45]
	v_pk_mul_f32 v[88:89], v[88:89], s[44:45]
	v_pk_mul_f32 v[90:91], v[90:91], s[44:45]
	v_pk_mul_f32 v[92:93], v[92:93], s[44:45]
	v_pk_mul_f32 v[94:95], v[94:95], s[44:45]
	v_cvt_pk_fp8_f32 v8, v64, v68
	v_cvt_pk_fp8_f32 v9, v72, v76
	v_cvt_pk_fp8_f32 v10, v80, v84
	v_cvt_pk_fp8_f32 v11, v88, v92
	v_and_b32_e32 v8, 0xffff, v8
	v_and_b32_e32 v10, 0xffff, v10
	v_lshl_or_b32 v176, v9, 16, v8
	v_lshl_or_b32 v177, v11, 16, v10
	global_store_dwordx2 v170, v[176:177], s[74:75]
	v_cvt_pk_fp8_f32 v8, v65, v69
	v_cvt_pk_fp8_f32 v9, v73, v77
	v_cvt_pk_fp8_f32 v10, v81, v85
	v_cvt_pk_fp8_f32 v11, v89, v93
	v_and_b32_e32 v8, 0xffff, v8
	v_and_b32_e32 v10, 0xffff, v10
	v_lshl_or_b32 v178, v9, 16, v8
	v_lshl_or_b32 v179, v11, 16, v10
	global_store_dwordx2 v171, v[178:179], s[74:75]
	v_cvt_pk_fp8_f32 v8, v66, v70
	v_cvt_pk_fp8_f32 v9, v74, v78
	v_cvt_pk_fp8_f32 v10, v82, v86
	v_cvt_pk_fp8_f32 v11, v90, v94
	v_and_b32_e32 v8, 0xffff, v8
	v_and_b32_e32 v10, 0xffff, v10
	v_lshl_or_b32 v180, v9, 16, v8
	v_lshl_or_b32 v181, v11, 16, v10
	global_store_dwordx2 v172, v[180:181], s[74:75]
	v_cvt_pk_fp8_f32 v8, v67, v71
	v_cvt_pk_fp8_f32 v9, v75, v79
	v_cvt_pk_fp8_f32 v10, v83, v87
	v_cvt_pk_fp8_f32 v11, v91, v95
	v_and_b32_e32 v8, 0xffff, v8
	v_and_b32_e32 v10, 0xffff, v10
	v_lshl_or_b32 v182, v9, 16, v8
	v_lshl_or_b32 v183, v11, 16, v10
	global_store_dwordx2 v173, v[182:183], s[74:75]
	s_add_u32 s47, s46, 0x800
	s_mul_hi_u32 s48, s47, 0xb60b61
	s_mul_i32 s49, s48, 0x168
	s_sub_u32 s49, s47, s49
	s_lshl_b32 s50, s48, 1
	s_or_b32 s50, s50, 1
	s_lshr_b32 s51, s49, 3
	s_and_b32 s52, s49, 7
	s_and_b32 s53, s52, 3
	s_lshr_b32 s54, s52, 2
	s_lshl_b32 s55, s53, 6
	s_lshl_b32 s56, s54, 5
	s_add_u32 s55, s55, s56
	s_bfe_u32 s56, s52, 0x10001
	s_lshl_b32 s56, s56, 7
	s_and_b32 s57, s52, 1
	s_lshl_b32 s57, s57, 5
	s_add_u32 s56, s56, s57
	s_lshl_b32 s57, s54, 6
	s_add_u32 s56, s56, s57
	s_lshl_b32 s57, s52, 5
	s_sub_u32 s58, s51, 9
	s_cmp_lt_u32 s58, 12
	s_cselect_b32 s57, s56, s57
	s_cmp_lt_u32 s51, 5
	s_cselect_b32 s57, s55, s57
	s_lshl_b32 s58, s51, 8
	s_add_u32 s57, s57, s58
	s_mul_i32 s58, s50, 0x2d0000
	s_lshl_b32 s57, s57, 2
	s_add_u32 s58, s58, s57
	s_add_u32 s60, s22, s58
	s_addc_u32 s61, s23, 0
	s_lshl_b32 s58, s49, 17
	s_lshl_b32 s59, s50, 6
	s_add_u32 s58, s58, s59
	s_add_u32 s74, s64, s58
	s_addc_u32 s75, s65, 0
	global_load_dwordx4 v[64:67], v162, s[60:61]
	global_load_dwordx4 v[68:71], v163, s[60:61]
	global_load_dwordx4 v[72:75], v164, s[60:61]
	global_load_dwordx4 v[76:79], v165, s[60:61]
	global_load_dwordx4 v[80:83], v166, s[60:61]
	global_load_dwordx4 v[84:87], v167, s[60:61]
	global_load_dwordx4 v[88:91], v168, s[60:61]
	global_load_dwordx4 v[92:95], v169, s[60:61]
	s_waitcnt vmcnt(20)
; #define LAS __attribute__((address_space(3)))
; __device__ __forceinline__ void transpose_item_fp8(const float* W, int N, unsigned char* W8, int pitch, int kofs, int k0, int n_src, int n_dst, float scale, LAS float* scr, int lane) {
;     const int r8 = lane >> 3, c4 = lane & 7;
;     f32x4 v[8];
; #pragma unroll
;     for (int i = 0; i < 8; ++i) v[i] = *(const f32x4*)(W + (size_t)(k0 + r8 + 8 * i) * N + n_src + 4 * c4);
; #pragma unroll
;     for (int i = 0; i < 8; ++i) { LAS float* d = scr + (r8 + 8 * i) * 33 + 4 * c4; d[0] = v[i][0]; d[1] = v[i][1]; d[2] = v[i][2]; d[3] = v[i][3]; }
;     asm volatile("s_waitcnt lgkmcnt(0)" ::: "memory");
;     const int n = lane & 31, cp = lane >> 5;
; #pragma unroll
;     for (int q = 0; q < 2; ++q) { const int ck = (2 * cp + q) * 16; const LAS float* sp = scr + ck * 33 + n; u32x4 o;
; #pragma unroll
;         for (int w = 0; w < 4; ++w) o[w] = pack_fp8x4(sp[(4 * w) * 33] * scale, sp[(4 * w + 1) * 33] * scale, sp[(4 * w + 2) * 33] * scale, sp[(4 * w + 3) * 33] * scale);
;         *(u32x4*)(W8 + (size_t)(n_dst + n) * pitch + kofs + k0 + ck) = o; }
	v_pk_mul_f32 v[96:97], v[96:97], s[44:45]
	v_pk_mul_f32 v[98:99], v[98:99], s[44:45]
	v_pk_mul_f32 v[100:101], v[100:101], s[44:45]
	v_pk_mul_f32 v[102:103], v[102:103], s[44:45]
	v_pk_mul_f32 v[104:105], v[104:105], s[44:45]
	v_pk_mul_f32 v[106:107], v[106:107], s[44:45]
	v_pk_mul_f32 v[108:109], v[108:109], s[44:45]
	v_pk_mul_f32 v[110:111], v[110:111], s[44:45]
	v_pk_mul_f32 v[112:113], v[112:113], s[44:45]
	v_pk_mul_f32 v[114:115], v[114:115], s[44:45]
	v_pk_mul_f32 v[116:117], v[116:117], s[44:45]
	v_pk_mul_f32 v[118:119], v[118:119], s[44:45]
	v_pk_mul_f32 v[120:121], v[120:121], s[44:45]
	v_pk_mul_f32 v[122:123], v[122:123], s[44:45]
	v_pk_mul_f32 v[124:125], v[124:125], s[44:45]
	v_pk_mul_f32 v[126:127], v[126:127], s[44:45]
	v_cvt_pk_fp8_f32 v8, v96, v100
	v_cvt_pk_fp8_f32 v9, v104, v108
	v_cvt_pk_fp8_f32 v10, v112, v116
	v_cvt_pk_fp8_f32 v11, v120, v124
	v_and_b32_e32 v8, 0xffff, v8
	v_and_b32_e32 v10, 0xffff, v10
	v_lshl_or_b32 v184, v9, 16, v8
	v_lshl_or_b32 v185, v11, 16, v10
	global_store_dwordx2 v170, v[184:185], s[76:77]
	v_cvt_pk_fp8_f32 v8, v97, v101
	v_cvt_pk_fp8_f32 v9, v105, v109
	v_cvt_pk_fp8_f32 v10, v113, v117
	v_cvt_pk_fp8_f32 v11, v121, v125
	v_and_b32_e32 v8, 0xffff, v8
	v_and_b32_e32 v10, 0xffff, v10
	v_lshl_or_b32 v186, v9, 16, v8
	v_lshl_or_b32 v187, v11, 16, v10
	global_store_dwordx2 v171, v[186:187], s[76:77]
	v_cvt_pk_fp8_f32 v8, v98, v102
	v_cvt_pk_fp8_f32 v9, v106, v110
	v_cvt_pk_fp8_f32 v10, v114, v118
	v_cvt_pk_fp8_f32 v11, v122, v126
	v_and_b32_e32 v8, 0xffff, v8
	v_and_b32_e32 v10, 0xffff, v10
	v_lshl_or_b32 v188, v9, 16, v8
	v_lshl_or_b32 v189, v11, 16, v10
	global_store_dwordx2 v172, v[188:189], s[76:77]
	v_cvt_pk_fp8_f32 v8, v99, v103
	v_cvt_pk_fp8_f32 v9, v107, v111
	v_cvt_pk_fp8_f32 v10, v115, v119
	v_cvt_pk_fp8_f32 v11, v123, v127
	v_and_b32_e32 v8, 0xffff, v8
	v_and_b32_e32 v10, 0xffff, v10
	v_lshl_or_b32 v190, v9, 16, v8
	v_lshl_or_b32 v191, v11, 16, v10
	global_store_dwordx2 v173, v[190:191], s[76:77]
	s_waitcnt vmcnt(16)
	v_pk_mul_f32 v[128:129], v[128:129], s[44:45]
	v_pk_mul_f32 v[130:131], v[130:131], s[44:45]
	v_pk_mul_f32 v[132:133], v[132:133], s[44:45]
	v_pk_mul_f32 v[134:135], v[134:135], s[44:45]
	v_pk_mul_f32 v[136:137], v[136:137], s[44:45]
	v_pk_mul_f32 v[138:139], v[138:139], s[44:45]
	v_pk_mul_f32 v[140:141], v[140:141], s[44:45]
	v_pk_mul_f32 v[142:143], v[142:143], s[44:45]
	v_pk_mul_f32 v[144:145], v[144:145], s[44:45]
	v_pk_mul_f32 v[146:147], v[146:147], s[44:45]
	v_pk_mul_f32 v[148:149], v[148:149], s[44:45]
	v_pk_mul_f32 v[150:151], v[150:151], s[44:45]
	v_pk_mul_f32 v[152:153], v[152:153], s[44:45]
	v_pk_mul_f32 v[154:155], v[154:155], s[44:45]
	v_pk_mul_f32 v[156:157], v[156:157], s[44:45]
	v_pk_mul_f32 v[158:159], v[158:159], s[44:45]
	v_cvt_pk_fp8_f32 v8, v128, v132
	v_cvt_pk_fp8_f32 v9, v136, v140
	v_cvt_pk_fp8_f32 v10, v144, v148
	v_cvt_pk_fp8_f32 v11, v152, v156
	v_and_b32_e32 v8, 0xffff, v8
	v_and_b32_e32 v10, 0xffff, v10
	v_lshl_or_b32 v176, v9, 16, v8
	v_lshl_or_b32 v177, v11, 16, v10
	global_store_dwordx2 v170, v[176:177], s[78:79]
	v_cvt_pk_fp8_f32 v8, v129, v133
	v_cvt_pk_fp8_f32 v9, v137, v141
	v_cvt_pk_fp8_f32 v10, v145, v149
	v_cvt_pk_fp8_f32 v11, v153, v157
	v_and_b32_e32 v8, 0xffff, v8
	v_and_b32_e32 v10, 0xffff, v10
	v_lshl_or_b32 v178, v9, 16, v8
	v_lshl_or_b32 v179, v11, 16, v10
	global_store_dwordx2 v171, v[178:179], s[78:79]
	v_cvt_pk_fp8_f32 v8, v130, v134
	v_cvt_pk_fp8_f32 v9, v138, v142
	v_cvt_pk_fp8_f32 v10, v146, v150
	v_cvt_pk_fp8_f32 v11, v154, v158
	v_and_b32_e32 v8, 0xffff, v8
	v_and_b32_e32 v10, 0xffff, v10
	v_lshl_or_b32 v180, v9, 16, v8
	v_lshl_or_b32 v181, v11, 16, v10
	global_store_dwordx2 v172, v[180:181], s[78:79]
	v_cvt_pk_fp8_f32 v8, v131, v135
	v_cvt_pk_fp8_f32 v9, v139, v143
	v_cvt_pk_fp8_f32 v10, v147, v151
	v_cvt_pk_fp8_f32 v11, v155, v159
	v_and_b32_e32 v8, 0xffff, v8
	v_and_b32_e32 v10, 0xffff, v10
	v_lshl_or_b32 v182, v9, 16, v8
	v_lshl_or_b32 v183, v11, 16, v10
	global_store_dwordx2 v173, v[182:183], s[78:79]
	s_waitcnt vmcnt(8)
	v_pk_mul_f32 v[64:65], v[64:65], s[44:45]
	v_pk_mul_f32 v[66:67], v[66:67], s[44:45]
	v_pk_mul_f32 v[68:69], v[68:69], s[44:45]
	v_pk_mul_f32 v[70:71], v[70:71], s[44:45]
	v_pk_mul_f32 v[72:73], v[72:73], s[44:45]
	v_pk_mul_f32 v[74:75], v[74:75], s[44:45]
	v_pk_mul_f32 v[76:77], v[76:77], s[44:45]
	v_pk_mul_f32 v[78:79], v[78:79], s[44:45]
	v_pk_mul_f32 v[80:81], v[80:81], s[44:45]
	v_pk_mul_f32 v[82:83], v[82:83], s[44:45]
	v_pk_mul_f32 v[84:85], v[84:85], s[44:45]
	v_pk_mul_f32 v[86:87], v[86:87], s[44:45]
	v_pk_mul_f32 v[88:89], v[88:89], s[44:45]
	v_pk_mul_f32 v[90:91], v[90:91], s[44:45]
	v_pk_mul_f32 v[92:93], v[92:93], s[44:45]
	v_pk_mul_f32 v[94:95], v[94:95], s[44:45]
	v_cvt_pk_fp8_f32 v8, v64, v68
	v_cvt_pk_fp8_f32 v9, v72, v76
	v_cvt_pk_fp8_f32 v10, v80, v84
	v_cvt_pk_fp8_f32 v11, v88, v92
	v_and_b32_e32 v8, 0xffff, v8
	v_and_b32_e32 v10, 0xffff, v10
	v_lshl_or_b32 v184, v9, 16, v8
	v_lshl_or_b32 v185, v11, 16, v10
	global_store_dwordx2 v170, v[184:185], s[74:75]
	v_cvt_pk_fp8_f32 v8, v65, v69
	v_cvt_pk_fp8_f32 v9, v73, v77
	v_cvt_pk_fp8_f32 v10, v81, v85
	v_cvt_pk_fp8_f32 v11, v89, v93
	v_and_b32_e32 v8, 0xffff, v8
	v_and_b32_e32 v10, 0xffff, v10
	v_lshl_or_b32 v186, v9, 16, v8
	v_lshl_or_b32 v187, v11, 16, v10
	global_store_dwordx2 v171, v[186:187], s[74:75]
	v_cvt_pk_fp8_f32 v8, v66, v70
	v_cvt_pk_fp8_f32 v9, v74, v78
	v_cvt_pk_fp8_f32 v10, v82, v86
	v_cvt_pk_fp8_f32 v11, v90, v94
	v_and_b32_e32 v8, 0xffff, v8
	v_and_b32_e32 v10, 0xffff, v10
	v_lshl_or_b32 v188, v9, 16, v8
	v_lshl_or_b32 v189, v11, 16, v10
	global_store_dwordx2 v172, v[188:189], s[74:75]
	v_cvt_pk_fp8_f32 v8, v67, v71
	v_cvt_pk_fp8_f32 v9, v75, v79
	v_cvt_pk_fp8_f32 v10, v83, v87
	v_cvt_pk_fp8_f32 v11, v91, v95
	v_and_b32_e32 v8, 0xffff, v8
	v_and_b32_e32 v10, 0xffff, v10
	v_lshl_or_b32 v190, v9, 16, v8
	v_lshl_or_b32 v191, v11, 16, v10
	global_store_dwordx2 v173, v[190:191], s[74:75]
; __device__ __forceinline__ unsigned cvt_pk_bf16(float lo, float hi) { unsigned r; asm volatile("v_cvt_pk_bf16_f32 %0, %1, %2" : "=v"(r) : "v"(lo), "v"(hi)); return r; }
; __global__ void __launch_bounds__(512, 2) hybrid_fwd(Args a) {
;     ...
;         const size_t gt = (size_t)bx * 512 + tid, GT = (size_t)G * 512;
;         {
;             const size_t NCH = (size_t)M * D / 8;
;             for (size_t i0 = gt; i0 < NCH; i0 += 4 * GT) {
;                 f32x4 v[4][2];
; #pragma unroll
;                 for (int u = 0; u < 4; ++u) { const size_t i = i0 + (size_t)u * GT; if (i < NCH) { v[u][0] = ((const f32x4*)a.x)[2 * i]; v[u][1] = ((const f32x4*)a.x)[2 * i + 1]; } }
; #pragma unroll
;                 for (int u = 0; u < 4; ++u) { const size_t i = i0 + (size_t)u * GT; if (i < NCH) {
;                     u32x4 w; w.x = cvt_pk_bf16(v[u][0][0], v[u][0][1]); w.y = cvt_pk_bf16(v[u][0][2], v[u][0][3]); w.z = cvt_pk_bf16(v[u][1][0], v[u][1][1]); w.w = cvt_pk_bf16(v[u][1][2], v[u][1][3]);
;                     if (a.n_bf16 > 0) ((u32x4*)XB)[i] = w;
;                     const unsigned p0 = pack_fp8x4(v[u][0][0], v[u][0][1], v[u][0][2], v[u][0][3]), p1 = pack_fp8x4(v[u][1][0], v[u][1][1], v[u][1][2], v[u][1][3]);
;                     ((u32x2*)XB8)[i] = (u32x2){p0, p1}; } }
.Lp0c_end:
	s_mov_b32 s100, 1
.Lp0_done:
	s_cmp_eq_u32 s100, 1
	s_cselect_b64 vcc, 0, vcc
	s_and_saveexec_b64 s[16:17], vcc
	s_cbranch_execz .LBB0_25
	s_load_dword s6, s[70:71], 0x1c0
	s_load_dwordx2 s[18:19], s[70:71], 0x0
	v_lshlrev_b32_e32 v2, 4, v160
	v_mov_b32_e32 v3, v161
	v_mov_b32_e32 v41, v161
	s_waitcnt lgkmcnt(0)
	s_cmp_gt_i32 s6, 0
	s_cselect_b64 s[20:21], -1, 0
	s_lshl_b64 s[6:7], s[2:3], 13
	v_lshl_add_u64 v[42:43], s[6:7], 0, v[2:3]
	s_lshl_b64 s[22:23], s[92:93], 15
	s_lshl_b64 s[6:7], s[2:3], 12
	s_lshl_b64 s[8:9], s[92:93], 12
	s_add_u32 s8, s6, s8
	s_addc_u32 s9, s7, s9
	s_lshl_b64 s[24:25], s[92:93], 14
	v_lshl_add_u64 v[46:47], s[6:7], 0, v[40:41]
	s_lshl_b64 s[26:27], s[92:93], 11
	s_lshl_b64 s[6:7], s[2:3], 14
	v_lshlrev_b32_e32 v2, 5, v160
	s_lshl_b64 s[28:29], s[92:93], 16
	s_lshl_b64 s[30:31], s[92:93], 10
	v_lshl_add_u64 v[48:49], s[6:7], 0, v[2:3]
	s_add_u32 s6, s4, s14
	s_addc_u32 s7, s5, s15
	v_lshl_add_u64 v[2:3], s[6:7], 0, v[160:161]
	s_add_u32 s6, s30, s4
	s_addc_u32 s7, s31, s5
	s_mul_i32 s34, s92, 0x600
	s_mul_hi_i32 s35, s92, 0x600
	s_add_u32 s4, s34, s4
	s_addc_u32 s5, s35, s5
	v_lshlrev_b64 v[50:51], 5, v[2:3]
	v_lshl_add_u64 v[4:5], s[6:7], 0, v[160:161]
	v_lshlrev_b64 v[58:59], 4, v[2:3]
	v_lshl_add_u64 v[2:3], s[4:5], 0, v[160:161]
	v_lshlrev_b64 v[52:53], 5, v[4:5]
	v_lshlrev_b64 v[60:61], 5, v[2:3]
	v_lshl_add_u64 v[44:45], s[8:9], 0, v[40:41]
	v_or_b32_e32 v52, 16, v52
	v_lshlrev_b64 v[54:55], 3, v[4:5]
	v_lshlrev_b64 v[56:57], 4, v[4:5]
	v_or_b32_e32 v60, 16, v60
	v_lshlrev_b64 v[62:63], 3, v[2:3]
	v_lshlrev_b64 v[64:65], 4, v[2:3]
	s_mov_b64 s[36:37], 0
	s_mov_b64 s[38:39], 0x3fffff
	v_mov_b64_e32 v[66:67], v[38:39]
	s_mov_b64 s[40:41], s[88:89]
	s_mov_b64 s[42:43], s[90:91]
	s_branch .LBB0_6

; __global__ void __launch_bounds__(512, 2) hybrid_fwd(Args a) {
;     ...
;         for (size_t i = gt; i < (size_t)M * 64; i += GT) {
;             const int t = (int)(i >> 6), j = (int)(i & 63);
;             const float ang = (float)a.pos[t] * a.inv_freq[j];
;             const double rev = (double)ang * 0.15915494309189535; const float fr = (float)(rev - __builtin_rint(rev));
;             const f32x2 cs = (f32x2){__builtin_amdgcn_cosf(fr), __builtin_amdgcn_sinf(fr)};
;             csB[i] = cs; if ((j & 1) == 0) csA[(size_t)t * 32 + (j >> 1)] = cs;
;         }
.LBB0_25:
	s_or_b64 exec, exec, s[16:17]
	s_add_u32 s12, s90, 0x8400000
	s_mov_b64 s[4:5], 0x100000
	v_and_b32_e32 v192, 63, v160
	s_addc_u32 s13, s91, 0
	v_cmp_gt_u64_e32 vcc, s[4:5], v[38:39]
	s_cmp_eq_u32 s100, 1
	s_cselect_b64 vcc, 0, vcc
	s_and_saveexec_b64 s[6:7], vcc
	s_cbranch_execz .LBB0_30
	v_lshlrev_b32_e32 v1, 2, v192
	global_load_dword v1, v1, s[70:71] offset:96
	s_load_dwordx2 s[8:9], s[70:71], 0x8
	s_lshl_b64 s[4:5], s[2:3], 12
	s_add_u32 s4, s90, s4
	v_and_b32_e32 v2, 1, v160
	v_mov_b32_e32 v41, 0
	s_addc_u32 s5, s91, s5
	v_cmp_eq_u32_e32 vcc, 0, v2
	v_lshl_add_u64 v[2:3], s[4:5], 0, v[40:41]
	s_mov_b64 s[4:5], 0x7c00000
	s_mov_b32 s18, 0x6dc9c883
	v_lshl_add_u64 v[2:3], v[2:3], 0, s[4:5]
	s_lshl_b64 s[10:11], s[92:93], 12
	s_mov_b64 s[16:17], 0
	s_mov_b32 s19, 0x3fc45f30
	s_mov_b64 s[20:21], 0xfffff
	s_branch .LBB0_28

; #define LAS __attribute__((address_space(3)))
; __global__ void __launch_bounds__(512, 2) hybrid_fwd(Args a) {
;     ...
;         LAS float* scr = (LAS float*)(lds + wave * 16384);
;         const int gw = bx * 8 + wave, NGW = G * 8;
;         constexpr int I_IN = (D / 64) * (DIN / 32);
;         for (int it = gw; it < I_IN; it += NGW) { const int nb = it % (DIN / 32), kb = it / (DIN / 32);
;             if ((a.fp8mask >> (nb >> 3)) & 1ull) transpose_item_fp8(a.w_in, DIN, (unsigned char*)WinT, 4096, 0, 64 * kb, gemm_col_to_orig(32 * nb), 32 * nb, W8_SCALE, scr, lane);
;             else transpose_item(a.w_in, DIN, WinT, D, 64 * kb, gemm_col_to_orig(32 * nb), 32 * nb, 0, scr, lane); }
.LBB0_30:
	s_or_b64 exec, exec, s[6:7]
	s_lshr_b32 s6, s33, 6
	s_add_u32 s14, s90, 0x4000000
	s_addc_u32 s15, s91, 0
	s_lshl_b32 s4, s6, 14
	s_add_i32 s31, s4, 0
	s_lshl_b32 s4, s2, 3
	s_mov_b32 s5, 0
	v_writelane_b32 v242, s6, 0
	s_add_i32 s6, s6, s4
	s_lshl_b32 s72, s92, 3
	s_mov_b32 s4, s6
	v_writelane_b32 v242, s4, 1
	s_cmpk_gt_i32 s6, 0x2cff
	v_and_b32_e32 v162, 32, v160
	v_writelane_b32 v242, s5, 2
	s_cbranch_scc1 .LBB0_52
	s_cmp_eq_u32 s100, 1
	s_cbranch_scc1 .LBB0_52
	s_load_dwordx2 s[6:7], s[70:71], 0x1c8
	s_load_dwordx2 s[8:9], s[70:71], 0x10
	v_and_b32_e32 v7, 7, v160
	v_lshrrev_b32_e32 v1, 3, v192
	v_lshlrev_b32_e32 v4, 4, v7
	v_and_b32_e32 v6, 31, v160
	v_mov_b32_e32 v5, 0
	v_add_u32_e32 v24, s31, v4
	v_mul_u32_u24_e32 v8, 0x84, v1
	v_lshl_add_u32 v23, v6, 2, s31
	v_mul_u32_u24_e32 v25, 0x84, v162
	v_or_b32_e32 v9, 8, v1
	s_waitcnt lgkmcnt(0)
	v_lshl_add_u64 v[2:3], s[8:9], 0, v[4:5]
	v_mul_u32_u24_e32 v26, 0x84, v9
	v_mul_u32_u24_e32 v7, 0x420, v7
	v_lshlrev_b32_e32 v9, 2, v1
	v_readlane_b32 s8, v242, 1
	v_add_u32_e32 v8, v24, v8
	v_add_u32_e32 v23, v23, v25
	v_mov_b32_e32 v163, v5
	v_lshl_add_u64 v[4:5], s[14:15], 0, v[4:5]
	v_add3_u32 v7, s31, v7, v9
	s_lshl_b32 s18, s8, 5
	s_lshl_b32 s19, s72, 5
	s_mov_b32 s20, 0xb400
	v_add_u32_e32 v9, 0x420, v8
	v_add_u32_e32 v10, 0x428, v8
	v_add_u32_e32 v11, 0x840, v8
	v_add_u32_e32 v12, 0x848, v8
	v_add_u32_e32 v13, 0xc60, v8
	v_add_u32_e32 v14, 0xc68, v8
	v_add_u32_e32 v15, 0x1080, v8
	v_add_u32_e32 v16, 0x1088, v8
	v_add_u32_e32 v17, 0x14a0, v8
	v_add_u32_e32 v18, 0x14a8, v8
	v_add_u32_e32 v19, 0x18c0, v8
	v_add_u32_e32 v20, 0x18c8, v8
	v_add_u32_e32 v21, 0x1ce0, v8
	v_add_u32_e32 v22, 0x1ce8, v8
	v_add_u32_e32 v24, v24, v26
	v_add_u32_e32 v25, 0x400, v23
	v_add_u32_e32 v26, 0x800, v23
	v_add_u32_e32 v27, 0xc00, v23
	s_mov_b32 s21, s8
	v_readlane_b32 s9, v242, 2
	s_branch .LBB0_35

; __global__ void __launch_bounds__(512, 2) hybrid_fwd(Args a) {
	.amdhsa_kernel _Z10hybrid_fwd4Args
		.amdhsa_group_segment_fixed_size 0
		.amdhsa_private_segment_fixed_size 0
		.amdhsa_kernarg_size 720
		.amdhsa_user_sgpr_count 2
		.amdhsa_user_sgpr_dispatch_ptr 0
		.amdhsa_user_sgpr_queue_ptr 0
		.amdhsa_user_sgpr_kernarg_segment_ptr 1
		.amdhsa_user_sgpr_dispatch_id 0
		.amdhsa_user_sgpr_kernarg_preload_length 0
		.amdhsa_user_sgpr_kernarg_preload_offset 0
		.amdhsa_user_sgpr_private_segment_size 0
		.amdhsa_uses_dynamic_stack 0
		.amdhsa_enable_private_segment 0
		.amdhsa_system_sgpr_workgroup_id_x 1
		.amdhsa_system_sgpr_workgroup_id_y 0
		.amdhsa_system_sgpr_workgroup_id_z 0
		.amdhsa_system_sgpr_workgroup_info 0
		.amdhsa_system_vgpr_workitem_id 2
		.amdhsa_next_free_vgpr 243
		.amdhsa_next_free_sgpr 101
		.amdhsa_accum_offset 244
		.amdhsa_reserve_vcc 1
		.amdhsa_float_round_mode_32 0
		.amdhsa_float_round_mode_16_64 0
		.amdhsa_float_denorm_mode_32 3
		.amdhsa_float_denorm_mode_16_64 3
		.amdhsa_dx10_clamp 1
		.amdhsa_ieee_mode 1
		.amdhsa_fp16_overflow 0
		.amdhsa_tg_split 0
		.amdhsa_exception_fp_ieee_invalid_op 0
		.amdhsa_exception_fp_denorm_src 0
		.amdhsa_exception_fp_ieee_div_zero 0
		.amdhsa_exception_fp_ieee_overflow 0
		.amdhsa_exception_fp_ieee_underflow 0
		.amdhsa_exception_fp_ieee_inexact 0
		.amdhsa_exception_int_div_zero 0
	.end_amdhsa_kernel

; __global__ void __launch_bounds__(512, 2) hybrid_fwd(Args a) {
amdhsa.kernels:
  - .agpr_count:     0
    .args:
      - .offset:         0
        .size:           464
        .value_kind:     by_value
      - .offset:         464
        .size:           4
        .value_kind:     hidden_block_count_x
      - .offset:         468
        .size:           4
        .value_kind:     hidden_block_count_y
      - .offset:         472
        .size:           4
        .value_kind:     hidden_block_count_z
      - .offset:         476
        .size:           2
        .value_kind:     hidden_group_size_x
      - .offset:         478
        .size:           2
        .value_kind:     hidden_group_size_y
      - .offset:         480
        .size:           2
        .value_kind:     hidden_group_size_z
      - .offset:         482
        .size:           2
        .value_kind:     hidden_remainder_x
      - .offset:         484
        .size:           2
        .value_kind:     hidden_remainder_y
      - .offset:         486
        .size:           2
        .value_kind:     hidden_remainder_z
      - .offset:         504
        .size:           8
        .value_kind:     hidden_global_offset_x
      - .offset:         512
        .size:           8
        .value_kind:     hidden_global_offset_y
      - .offset:         520
        .size:           8
        .value_kind:     hidden_global_offset_z
      - .offset:         528
        .size:           2
        .value_kind:     hidden_grid_dims
      - .offset:         552
        .size:           8
        .value_kind:     hidden_multigrid_sync_arg
      - .offset:         584
        .size:           4
        .value_kind:     hidden_dynamic_lds_size
    .group_segment_fixed_size: 0
    .kernarg_segment_align: 8
    .kernarg_segment_size: 720
    .language:       OpenCL C
    .language_version:
      - 2
      - 0
    .max_flat_workgroup_size: 512
    .name:           _Z10hybrid_fwd4Args
    .private_segment_fixed_size: 0
    .sgpr_count:     107
    .sgpr_spill_count: 36
    .symbol:         _Z10hybrid_fwd4Args.kd
    .uniform_work_group_size: 1
    .uses_dynamic_stack: false
    .vgpr_count:     243
    .vgpr_spill_count: 0
    .wavefront_size: 64
